# v38combined
# speedup vs baseline: 1.0007x; 1.0007x over previous
; __device__ __forceinline__ float bf2f(u16 b) { return __uint_as_float(((unsigned)b) << 16); }
; __device__ __forceinline__ float silu_f(float g) { return g * __builtin_amdgcn_rcpf(1.f + __builtin_amdgcn_exp2f(-g * LOG2E)); }
; template <int EPI>
; __device__ __forceinline__ void epilogue(const Params& p, int pass, int layer, int pm, int pn,
;                                          f32x4 (&acc)[2][2][4][2], const float* xin, float* xout) {
;     ...
;     int t0 = pm * 256;
;     u16* Y = (u16*)(p.ws + OFF_Y);
;     const float* stat = (const float*)(p.ws + OFF_STAT0);
;     int h = pn >> 1;
;     float gn[2][2];
; #pragma unroll
;     for (int bj = 0; bj < 2; ++bj)
; #pragma unroll
;       for (int n = 0; n < 2; ++n) gn[bj][n] = p.ret_gn[pn * 256 + bj * 128 + wc * 32 + n * 16 + fr];
; #pragma unroll
;     for (int ai = 0; ai < 2; ++ai)
; #pragma unroll
;       for (int m = 0; m < 4; ++m) {
;         int tb = t0 + ai * 128 + wr * 64 + m * 16 + fq * 4;
;         asm volatile("" : "+v"(tb));
;         float4 s01[4], s23[4];
;         u16 yv[4][2][2];
; #pragma unroll
;         for (int j = 0; j < 4; ++j) {
;           const float4* sp = (const float4*)(stat + ((long)(tb + j) * 8 + h) * 8);
;           s01[j] = sp[0]; s23[j] = sp[1];
; #pragma unroll
;           for (int bj = 0; bj < 2; ++bj)
; #pragma unroll
;             for (int n = 0; n < 2; ++n)
;               yv[j][bj][n] = Y[(long)(tb + j) * YS + pn * 256 + bj * 128 + wc * 32 + n * 16 + fr];
;         }
; #pragma unroll
;         for (int j = 0; j < 4; ++j) {
;           float s1 = s01[j].x + s01[j].z + s23[j].x + s23[j].z, s2 = s01[j].y + s01[j].w + s23[j].y + s23[j].w;
;           float mu = s1 * (1.f / 512.f);
;           float var = s2 * (1.f / 512.f) - mu * mu;
;           float rstd = rsqrtf(fmaxf(var, 0.f) + 1e-5f);
; #pragma unroll
;           for (int bj = 0; bj < 2; ++bj)
; #pragma unroll
;             for (int n = 0; n < 2; ++n) {
;               float g = acc[ai][bj][m][n][j];
;               float yn = (bf2f(yv[j][bj][n]) - mu) * rstd * gn[bj][n];
;               Y[(long)(tb + j) * YS + pn * 256 + bj * 128 + wc * 32 + n * 16 + fr] = f2bf(silu_f(g) * yn);
;             }
.LBB0_54:
	v_mbcnt_lo_u32_b32 v0, -1, 0
	v_mbcnt_hi_u32_b32 v0, -1, v0
	s_lshl_b32 s18, s3, 8
	v_or_b32_e32 v132, s33, v0
	v_lshrrev_b32_e32 v130, 1, v132
	v_and_b32_e32 v133, 15, v0
	v_and_b32_e32 v134, 0x60, v130
	s_lshl_b32 s1, s14, 8
	s_ashr_i32 s14, s3, 1
	v_or3_b32 v130, v133, s18, v134
	v_readlane_b32 s40, v252, 16
	v_lshrrev_b32_e32 v0, 2, v0
	s_ashr_i32 s15, s14, 31
	v_ashrrev_i32_e32 v131, 31, v130
	v_readlane_b32 s54, v252, 30
	v_readlane_b32 s55, v252, 31
	v_and_or_b32 v0, v0, 12, s1
	s_lshl_b64 s[14:15], s[14:15], 5
	v_readlane_b32 s1, v252, 59
	v_lshl_add_u64 v[130:131], v[130:131], 2, s[54:55]
	s_add_u32 s16, s1, s14
	v_readlane_b32 s1, v252, 60
	global_load_dword v151, v[130:131], off
	global_load_dword v150, v[130:131], off offset:64
	global_load_dword v149, v[130:131], off offset:512
	global_load_dword v148, v[130:131], off offset:576
	v_ashrrev_i32_e32 v130, 2, v132
	s_addc_u32 s17, s1, s15
	s_ashr_i32 s19, s18, 31
	v_and_b32_e32 v130, 0xffffffc0, v130
	s_lshl_b64 s[14:15], s[18:19], 1
	v_readlane_b32 s18, v252, 61
	v_add_u32_e32 v152, v0, v130
	v_readlane_b32 s19, v252, 62
	s_add_u32 s14, s18, s14
	s_addc_u32 s15, s19, s15
	v_lshlrev_b32_e32 v0, 1, v134
	v_mov_b32_e32 v134, v152
	v_lshl_add_u64 v[130:131], s[14:15], 0, v[0:1]
	v_lshlrev_b32_e32 v0, 1, v133
	v_lshl_add_u64 v[138:139], v[130:131], 0, v[0:1]
	v_ashrrev_i32_e32 v135, 31, v134
	v_lshlrev_b64 v[130:131], 8, v[134:135]
	v_lshl_add_u64 v[136:137], s[16:17], 0, v[130:131]
	global_load_dwordx4 v[154:157], v[136:137], off offset:16
	global_load_dwordx4 v[158:161], v[136:137], off
	s_mov_b32 s18, 0x3b000000
	v_mad_i64_i32 v[142:143], s[14:15], v134, s24, v[138:139]
	global_load_ushort v162, v[142:143], off
	global_load_ushort v163, v[142:143], off offset:32
	global_load_ushort v164, v[142:143], off offset:256
	global_load_ushort v165, v[142:143], off offset:288
	v_mul_f32_e32 v153, 0xbfb8aa3b, v126
	v_exp_f32_e32 v153, v153
	v_add_u32_e32 v130, 1, v134
	v_ashrrev_i32_e32 v131, 31, v130
	v_lshlrev_b64 v[132:133], 8, v[130:131]
	v_add_f32_e32 v153, 1.0, v153
	v_rcp_f32_e32 v153, v153
	v_lshl_add_u64 v[132:133], s[16:17], 0, v[132:133]
	global_load_dwordx4 v[194:197], v[132:133], off offset:16
	global_load_dwordx4 v[198:201], v[132:133], off
	v_mad_i64_i32 v[144:145], s[14:15], v130, s24, v[138:139]
	global_load_ushort v166, v[144:145], off
	global_load_ushort v167, v[144:145], off offset:32
	global_load_ushort v168, v[144:145], off offset:256
	global_load_ushort v169, v[144:145], off offset:288
	v_mul_f32_e32 v126, v126, v153
	v_mul_f32_e32 v153, 0xbfb8aa3b, v122
	v_exp_f32_e32 v153, v153
	v_add_u32_e32 v140, 2, v134
	v_ashrrev_i32_e32 v141, 31, v140
	v_lshlrev_b64 v[130:131], 8, v[140:141]
	v_add_f32_e32 v153, 1.0, v153
	v_rcp_f32_e32 v153, v153
	v_lshl_add_u64 v[130:131], s[16:17], 0, v[130:131]
	global_load_dwordx4 v[202:205], v[130:131], off offset:16
	global_load_dwordx4 v[206:209], v[130:131], off
	v_mad_i64_i32 v[146:147], s[14:15], v140, s24, v[138:139]
	global_load_ushort v170, v[146:147], off
	global_load_ushort v171, v[146:147], off offset:32
	global_load_ushort v172, v[146:147], off offset:256
	global_load_ushort v173, v[146:147], off offset:288
	v_mul_f32_e32 v122, v122, v153
	v_mul_f32_e32 v153, 0xbfb8aa3b, v118
	v_exp_f32_e32 v153, v153
	v_add_u32_e32 v140, 3, v134
	v_ashrrev_i32_e32 v141, 31, v140
	v_lshlrev_b64 v[134:135], 8, v[140:141]
	v_add_f32_e32 v153, 1.0, v153
	v_rcp_f32_e32 v153, v153
	v_lshl_add_u64 v[134:135], s[16:17], 0, v[134:135]
	global_load_dwordx4 v[210:213], v[134:135], off offset:16
	global_load_dwordx4 v[214:217], v[134:135], off
	v_mad_i64_i32 v[140:141], s[14:15], v140, s24, v[138:139]
	global_load_ushort v174, v[140:141], off
	global_load_ushort v175, v[140:141], off offset:32
	global_load_ushort v176, v[140:141], off offset:256
	global_load_ushort v177, v[140:141], off offset:288
	v_mul_f32_e32 v118, v118, v153
	s_mov_b32 s3, s0
	v_readlane_b32 s41, v252, 17
	v_readlane_b32 s42, v252, 18
	v_readlane_b32 s43, v252, 19
	v_readlane_b32 s44, v252, 20
	v_readlane_b32 s45, v252, 21
	v_readlane_b32 s46, v252, 22
	v_readlane_b32 s47, v252, 23
	v_readlane_b32 s48, v252, 24
	v_readlane_b32 s49, v252, 25
	v_readlane_b32 s50, v252, 26
	v_readlane_b32 s51, v252, 27
	v_readlane_b32 s52, v252, 28
	v_readlane_b32 s53, v252, 29
	s_waitcnt vmcnt(22)
	v_pk_add_f32 v[136:137], v[158:159], v[160:161]
	s_nop 0
	v_pk_add_f32 v[136:137], v[136:137], v[154:155]
	s_nop 0
	v_pk_add_f32 v[136:137], v[136:137], v[156:157]
	s_nop 0
	v_pk_mul_f32 v[136:137], v[136:137], s[18:19] op_sel_hi:[1,0]
	s_nop 0
	v_fma_f32 v0, -v136, v136, v137
	v_max_f32_e32 v0, 0, v0
	v_add_f32_e32 v0, 0x3727c5ac, v0
	v_cmp_gt_f32_e32 vcc, s25, v0
	v_mul_f32_e32 v137, 0x4b800000, v0
	s_nop 0
	v_cndmask_b32_e32 v0, v0, v137, vcc
	v_rsq_f32_e32 v0, v0
	s_nop 0
	v_mul_f32_e32 v137, 0x45800000, v0
	v_cndmask_b32_e32 v137, v0, v137, vcc
	s_waitcnt vmcnt(21)
	v_lshlrev_b32_e32 v0, 16, v162
	v_sub_f32_e32 v0, v0, v136
	v_mul_f32_e32 v0, v0, v137
	v_mul_f32_e32 v0, v151, v0
	v_mul_f32_e32 v0, v126, v0
	v_cvt_pk_bf16_f32 v0, v0, s0
	s_waitcnt vmcnt(20)
	v_lshlrev_b32_e32 v126, 16, v163
	v_sub_f32_e32 v126, v126, v136
	v_mul_f32_e32 v126, v126, v137
	v_mul_f32_e32 v126, v150, v126
	v_mul_f32_e32 v122, v122, v126
	v_cvt_pk_bf16_f32 v122, v122, s0
	s_waitcnt vmcnt(19)
	v_lshlrev_b32_e32 v126, 16, v164
	v_sub_f32_e32 v126, v126, v136
	v_mul_f32_e32 v126, v126, v137
	v_mul_f32_e32 v126, v149, v126
	v_mul_f32_e32 v118, v118, v126
	v_cvt_pk_bf16_f32 v118, v118, s0
	s_waitcnt vmcnt(18)
	v_lshlrev_b32_e32 v126, 16, v165
	v_sub_f32_e32 v126, v126, v136
	v_mul_f32_e32 v136, 0xbfb8aa3b, v114
	v_exp_f32_e32 v136, v136
	s_waitcnt vmcnt(16)
; __device__ __forceinline__ float bf2f(u16 b) { return __uint_as_float(((unsigned)b) << 16); }
; __device__ __forceinline__ float silu_f(float g) { return g * __builtin_amdgcn_rcpf(1.f + __builtin_amdgcn_exp2f(-g * LOG2E)); }
; template <int EPI>
; __device__ __forceinline__ void epilogue(const Params& p, int pass, int layer, int pm, int pn,
;                                          f32x4 (&acc)[2][2][4][2], const float* xin, float* xout) {
;     ...
;         for (int j = 0; j < 4; ++j) {
;           float s1 = s01[j].x + s01[j].z + s23[j].x + s23[j].z, s2 = s01[j].y + s01[j].w + s23[j].y + s23[j].w;
;           float mu = s1 * (1.f / 512.f);
;           float var = s2 * (1.f / 512.f) - mu * mu;
;           float rstd = rsqrtf(fmaxf(var, 0.f) + 1e-5f);
; #pragma unroll
;           for (int bj = 0; bj < 2; ++bj)
; #pragma unroll
;             for (int n = 0; n < 2; ++n) {
;               float g = acc[ai][bj][m][n][j];
;               float yn = (bf2f(yv[j][bj][n]) - mu) * rstd * gn[bj][n];
;               Y[(long)(tb + j) * YS + pn * 256 + bj * 128 + wc * 32 + n * 16 + fr] = f2bf(silu_f(g) * yn);
;             }
	v_pk_add_f32 v[132:133], v[198:199], v[200:201]
	v_mul_f32_e32 v126, v126, v137
	v_pk_add_f32 v[132:133], v[132:133], v[194:195]
	v_add_f32_e32 v136, 1.0, v136
	v_rcp_f32_e32 v136, v136
	v_mul_f32_e32 v126, v148, v126
	v_pk_add_f32 v[132:133], v[132:133], v[196:197]
	v_mul_f32_e32 v114, v114, v136
	v_mul_f32_e32 v114, v114, v126
	v_pk_mul_f32 v[132:133], v[132:133], s[18:19] op_sel_hi:[1,0]
	v_cvt_pk_bf16_f32 v126, v114, s0
	v_fma_f32 v114, -v132, v132, v133
	v_max_f32_e32 v114, 0, v114
	v_add_f32_e32 v114, 0x3727c5ac, v114
	v_cmp_gt_f32_e32 vcc, s25, v114
	v_mul_f32_e32 v133, 0x4b800000, v114
	v_mul_f32_e32 v136, 0xbfb8aa3b, v127
	v_cndmask_b32_e32 v114, v114, v133, vcc
	v_rsq_f32_e32 v114, v114
	v_exp_f32_e32 v136, v136
	v_mul_f32_e32 v133, 0x45800000, v114
	v_cndmask_b32_e32 v114, v114, v133, vcc
	v_add_f32_e32 v136, 1.0, v136
	v_rcp_f32_e32 v136, v136
	s_waitcnt vmcnt(15)
	v_lshlrev_b32_e32 v133, 16, v166
	v_sub_f32_e32 v133, v133, v132
	v_mul_f32_e32 v133, v133, v114
	v_mul_f32_e32 v133, v151, v133
	v_mul_f32_e32 v127, v127, v136
	v_mul_f32_e32 v127, v127, v133
	v_mul_f32_e32 v136, 0xbfb8aa3b, v123
	v_exp_f32_e32 v136, v136
	v_cvt_pk_bf16_f32 v127, v127, s0
	v_add_f32_e32 v136, 1.0, v136
	v_rcp_f32_e32 v136, v136
	s_waitcnt vmcnt(14)
	v_lshlrev_b32_e32 v133, 16, v167
	v_sub_f32_e32 v133, v133, v132
	v_mul_f32_e32 v133, v133, v114
	v_mul_f32_e32 v133, v150, v133
	v_mul_f32_e32 v123, v123, v136
	v_mul_f32_e32 v123, v123, v133
	v_mul_f32_e32 v136, 0xbfb8aa3b, v119
	v_exp_f32_e32 v136, v136
	v_cvt_pk_bf16_f32 v123, v123, s0
	v_add_f32_e32 v136, 1.0, v136
	v_rcp_f32_e32 v136, v136
	s_waitcnt vmcnt(13)
	v_lshlrev_b32_e32 v133, 16, v168
	v_sub_f32_e32 v133, v133, v132
	v_mul_f32_e32 v133, v133, v114
	v_mul_f32_e32 v133, v149, v133
	v_mul_f32_e32 v119, v119, v136
	v_mul_f32_e32 v119, v119, v133
	v_cvt_pk_bf16_f32 v119, v119, s0
	s_waitcnt vmcnt(12)
	v_lshlrev_b32_e32 v133, 16, v169
	v_sub_f32_e32 v132, v133, v132
	v_mul_f32_e32 v114, v132, v114
	v_mul_f32_e32 v132, 0xbfb8aa3b, v115
	v_exp_f32_e32 v132, v132
	v_mul_f32_e32 v114, v148, v114
	v_add_f32_e32 v132, 1.0, v132
	v_rcp_f32_e32 v132, v132
	s_nop 0
	v_mul_f32_e32 v115, v115, v132
	s_nop 0
	v_mul_f32_e32 v114, v115, v114
	v_cvt_pk_bf16_f32 v153, v114, s0
	s_waitcnt vmcnt(10)
	v_pk_add_f32 v[114:115], v[206:207], v[208:209]
	s_nop 0
	v_pk_add_f32 v[114:115], v[114:115], v[202:203]
	v_mul_f32_e32 v131, 0xbfb8aa3b, v128
	v_pk_add_f32 v[114:115], v[114:115], v[204:205]
	v_exp_f32_e32 v131, v131
	v_pk_mul_f32 v[114:115], v[114:115], s[18:19] op_sel_hi:[1,0]
	v_add_f32_e32 v131, 1.0, v131
	v_fma_f32 v115, -v114, v114, v115
	v_max_f32_e32 v115, 0, v115
	v_add_f32_e32 v115, 0x3727c5ac, v115
	v_cmp_gt_f32_e32 vcc, s25, v115
	v_mul_f32_e32 v130, 0x4b800000, v115
	v_rcp_f32_e32 v131, v131
	v_cndmask_b32_e32 v115, v115, v130, vcc
	v_rsq_f32_e32 v115, v115
	v_mul_f32_e32 v128, v128, v131
	v_mul_f32_e32 v131, 0xbfb8aa3b, v124
	v_mul_f32_e32 v130, 0x45800000, v115
	v_cndmask_b32_e32 v130, v115, v130, vcc
	v_exp_f32_e32 v131, v131
	s_waitcnt vmcnt(9)
	v_lshlrev_b32_e32 v115, 16, v170
	v_sub_f32_e32 v115, v115, v114
	v_mul_f32_e32 v115, v115, v130
	v_mul_f32_e32 v115, v151, v115
	v_mul_f32_e32 v115, v128, v115
	v_add_f32_e32 v131, 1.0, v131
	v_rcp_f32_e32 v131, v131
	v_cvt_pk_bf16_f32 v115, v115, s0
	v_mul_f32_e32 v124, v124, v131
	v_mul_f32_e32 v131, 0xbfb8aa3b, v120
	v_exp_f32_e32 v131, v131
	s_waitcnt vmcnt(8)
	v_lshlrev_b32_e32 v128, 16, v171
	v_sub_f32_e32 v128, v128, v114
	v_mul_f32_e32 v128, v128, v130
	v_mul_f32_e32 v128, v150, v128
	v_mul_f32_e32 v124, v124, v128
	v_add_f32_e32 v131, 1.0, v131
	v_rcp_f32_e32 v131, v131
	v_cvt_pk_bf16_f32 v124, v124, s0
	v_mul_f32_e32 v120, v120, v131
	s_waitcnt vmcnt(7)
	v_lshlrev_b32_e32 v128, 16, v172
	v_sub_f32_e32 v128, v128, v114
	v_mul_f32_e32 v128, v128, v130
	v_mul_f32_e32 v128, v149, v128
	v_mul_f32_e32 v120, v120, v128
	v_cvt_pk_bf16_f32 v120, v120, s0
	s_waitcnt vmcnt(6)
	v_lshlrev_b32_e32 v128, 16, v173
	v_sub_f32_e32 v114, v128, v114
	v_mul_f32_e32 v128, 0xbfb8aa3b, v116
	v_exp_f32_e32 v128, v128
	v_mul_f32_e32 v114, v114, v130
	v_mul_f32_e32 v114, v148, v114
	v_add_f32_e32 v128, 1.0, v128
	v_rcp_f32_e32 v128, v128
	s_nop 0
	v_mul_f32_e32 v116, v116, v128
	v_mul_f32_e32 v114, v116, v114
	s_nop 0
	s_nop 0
	v_cvt_pk_bf16_f32 v114, v114, s0
	global_store_short v[142:143], v0, off
	global_store_short v[142:143], v122, off offset:32
	global_store_short v[142:143], v118, off offset:256
	global_store_short v[142:143], v126, off offset:288
	global_store_short v[144:145], v127, off
	global_store_short v[144:145], v123, off offset:32
	global_store_short v[144:145], v119, off offset:256
	global_store_short v[144:145], v153, off offset:288
	global_store_short v[146:147], v115, off
	global_store_short v[146:147], v124, off offset:32
	global_store_short v[146:147], v120, off offset:256
	global_store_short v[146:147], v114, off offset:288
	v_or_b32_e32 v118, 16, v152
	s_waitcnt vmcnt(16)
	v_pk_add_f32 v[114:115], v[214:215], v[216:217]
	s_nop 0
	v_pk_add_f32 v[114:115], v[114:115], v[210:211]
	s_nop 0
	v_pk_add_f32 v[114:115], v[114:115], v[212:213]
	s_nop 0
	v_pk_mul_f32 v[114:115], v[114:115], s[18:19] op_sel_hi:[1,0]
	s_nop 0
	v_fma_f32 v0, -v114, v114, v115
	v_max_f32_e32 v0, 0, v0
	v_add_f32_e32 v0, 0x3727c5ac, v0
	v_cmp_gt_f32_e32 vcc, s25, v0
	v_mul_f32_e32 v115, 0x4b800000, v0
	s_nop 0
	v_cndmask_b32_e32 v0, v0, v115, vcc
	v_rsq_f32_e32 v0, v0
	s_nop 0
	v_mul_f32_e32 v115, 0x45800000, v0
	v_cndmask_b32_e32 v0, v0, v115, vcc
	s_waitcnt vmcnt(15)
; __device__ __forceinline__ float bf2f(u16 b) { return __uint_as_float(((unsigned)b) << 16); }
; __device__ __forceinline__ float silu_f(float g) { return g * __builtin_amdgcn_rcpf(1.f + __builtin_amdgcn_exp2f(-g * LOG2E)); }
; template <int EPI>
; __device__ __forceinline__ void epilogue(const Params& p, int pass, int layer, int pm, int pn,
;                                          f32x4 (&acc)[2][2][4][2], const float* xin, float* xout) {
;     ...
;         int tb = t0 + ai * 128 + wr * 64 + m * 16 + fq * 4;
;         asm volatile("" : "+v"(tb));
;         float4 s01[4], s23[4];
;         u16 yv[4][2][2];
; #pragma unroll
;         for (int j = 0; j < 4; ++j) {
;           const float4* sp = (const float4*)(stat + ((long)(tb + j) * 8 + h) * 8);
;           s01[j] = sp[0]; s23[j] = sp[1];
; #pragma unroll
;           for (int bj = 0; bj < 2; ++bj)
; #pragma unroll
;             for (int n = 0; n < 2; ++n)
;               yv[j][bj][n] = Y[(long)(tb + j) * YS + pn * 256 + bj * 128 + wc * 32 + n * 16 + fr];
;         }
; #pragma unroll
;         for (int j = 0; j < 4; ++j) {
;           float s1 = s01[j].x + s01[j].z + s23[j].x + s23[j].z, s2 = s01[j].y + s01[j].w + s23[j].y + s23[j].w;
;           float mu = s1 * (1.f / 512.f);
;           float var = s2 * (1.f / 512.f) - mu * mu;
;           float rstd = rsqrtf(fmaxf(var, 0.f) + 1e-5f);
; #pragma unroll
;           for (int bj = 0; bj < 2; ++bj)
; #pragma unroll
;             for (int n = 0; n < 2; ++n) {
;               float g = acc[ai][bj][m][n][j];
;               float yn = (bf2f(yv[j][bj][n]) - mu) * rstd * gn[bj][n];
;               Y[(long)(tb + j) * YS + pn * 256 + bj * 128 + wc * 32 + n * 16 + fr] = f2bf(silu_f(g) * yn);
;             }
	v_lshlrev_b32_e32 v115, 16, v174
	v_mul_f32_e32 v116, 0xbfb8aa3b, v129
	v_exp_f32_e32 v116, v116
	v_sub_f32_e32 v115, v115, v114
	v_mul_f32_e32 v115, v115, v0
	v_mul_f32_e32 v115, v151, v115
	v_add_f32_e32 v116, 1.0, v116
	v_rcp_f32_e32 v116, v116
	s_nop 0
	v_mul_f32_e32 v116, v129, v116
	v_mul_f32_e32 v115, v116, v115
	v_mul_f32_e32 v116, 0xbfb8aa3b, v125
	v_exp_f32_e32 v116, v116
	v_cvt_pk_bf16_f32 v115, v115, s0
	global_store_short v[140:141], v115, off
	s_waitcnt vmcnt(15)
	v_lshlrev_b32_e32 v115, 16, v175
	v_add_f32_e32 v116, 1.0, v116
	v_rcp_f32_e32 v116, v116
	v_sub_f32_e32 v115, v115, v114
	v_mul_f32_e32 v115, v115, v0
	v_mul_f32_e32 v115, v150, v115
	v_mul_f32_e32 v116, v125, v116
	v_mul_f32_e32 v115, v116, v115
	v_mul_f32_e32 v116, 0xbfb8aa3b, v121
	v_exp_f32_e32 v116, v116
	v_cvt_pk_bf16_f32 v115, v115, s0
	global_store_short v[140:141], v115, off offset:32
	s_waitcnt vmcnt(15)
	v_lshlrev_b32_e32 v115, 16, v176
	v_add_f32_e32 v116, 1.0, v116
	v_rcp_f32_e32 v116, v116
	v_sub_f32_e32 v115, v115, v114
	v_mul_f32_e32 v115, v115, v0
	v_mul_f32_e32 v115, v149, v115
	v_mul_f32_e32 v116, v121, v116
	v_mul_f32_e32 v115, v116, v115
	v_cvt_pk_bf16_f32 v115, v115, s0
	global_store_short v[140:141], v115, off offset:256
	s_waitcnt vmcnt(15)
	v_lshlrev_b32_e32 v115, 16, v177
	v_sub_f32_e32 v114, v115, v114
	v_mul_f32_e32 v0, v114, v0
	v_mul_f32_e32 v114, 0xbfb8aa3b, v117
	v_exp_f32_e32 v114, v114
	v_mul_f32_e32 v0, v148, v0
	v_add_f32_e32 v114, 1.0, v114
	v_rcp_f32_e32 v114, v114
	s_nop 0
	v_mul_f32_e32 v114, v117, v114
	v_mul_f32_e32 v0, v114, v0
	v_cvt_pk_bf16_f32 v0, v0, s0
	global_store_short v[140:141], v0, off offset:288
	s_nop 0
	v_ashrrev_i32_e32 v119, 31, v118
	v_lshlrev_b64 v[114:115], 8, v[118:119]
	v_lshl_add_u64 v[120:121], s[16:17], 0, v[114:115]
	global_load_dwordx4 v[130:133], v[120:121], off offset:16
	global_load_dwordx4 v[134:137], v[120:121], off
	v_mad_i64_i32 v[124:125], s[14:15], v118, s24, v[138:139]
	global_load_ushort v178, v[124:125], off
	global_load_ushort v179, v[124:125], off offset:32
	global_load_ushort v180, v[124:125], off offset:256
	global_load_ushort v181, v[124:125], off offset:288
	v_add_u32_e32 v114, 1, v118
	v_ashrrev_i32_e32 v115, 31, v114
	v_lshlrev_b64 v[116:117], 8, v[114:115]
	v_lshl_add_u64 v[116:117], s[16:17], 0, v[116:117]
	global_load_dwordx4 v[194:197], v[116:117], off offset:16
	global_load_dwordx4 v[198:201], v[116:117], off
	v_mad_i64_i32 v[126:127], s[14:15], v114, s24, v[138:139]
	global_load_ushort v182, v[126:127], off
	global_load_ushort v183, v[126:127], off offset:32
	global_load_ushort v184, v[126:127], off offset:256
	global_load_ushort v185, v[126:127], off offset:288
	v_add_u32_e32 v122, 2, v118
	v_ashrrev_i32_e32 v123, 31, v122
	v_lshlrev_b64 v[114:115], 8, v[122:123]
	v_lshl_add_u64 v[114:115], s[16:17], 0, v[114:115]
	global_load_dwordx4 v[202:205], v[114:115], off offset:16
	global_load_dwordx4 v[206:209], v[114:115], off
	v_mad_i64_i32 v[128:129], s[14:15], v122, s24, v[138:139]
	global_load_ushort v186, v[128:129], off
	global_load_ushort v187, v[128:129], off offset:32
	global_load_ushort v188, v[128:129], off offset:256
	global_load_ushort v189, v[128:129], off offset:288
	v_add_u32_e32 v122, 3, v118
	v_ashrrev_i32_e32 v123, 31, v122
	v_lshlrev_b64 v[118:119], 8, v[122:123]
	v_lshl_add_u64 v[118:119], s[16:17], 0, v[118:119]
	global_load_dwordx4 v[210:213], v[118:119], off offset:16
	global_load_dwordx4 v[214:217], v[118:119], off
	v_mad_i64_i32 v[122:123], s[14:15], v122, s24, v[138:139]
	global_load_ushort v190, v[122:123], off
	global_load_ushort v191, v[122:123], off offset:32
	global_load_ushort v192, v[122:123], off offset:256
	global_load_ushort v193, v[122:123], off offset:288
	s_waitcnt vmcnt(22)
	v_pk_add_f32 v[120:121], v[134:135], v[136:137]
	s_nop 0
	v_pk_add_f32 v[120:121], v[120:121], v[130:131]
	v_mul_f32_e32 v130, 0xbfb8aa3b, v110
	v_pk_add_f32 v[120:121], v[120:121], v[132:133]
	v_exp_f32_e32 v130, v130
	v_pk_mul_f32 v[120:121], v[120:121], s[18:19] op_sel_hi:[1,0]
	v_add_f32_e32 v130, 1.0, v130
	v_fma_f32 v0, -v120, v120, v121
	v_max_f32_e32 v0, 0, v0
	v_add_f32_e32 v0, 0x3727c5ac, v0
	v_cmp_gt_f32_e32 vcc, s25, v0
	v_mul_f32_e32 v121, 0x4b800000, v0
	v_rcp_f32_e32 v130, v130
	v_cndmask_b32_e32 v0, v0, v121, vcc
	v_rsq_f32_e32 v0, v0
	v_mul_f32_e32 v110, v110, v130
	v_mul_f32_e32 v130, 0xbfb8aa3b, v106
	v_mul_f32_e32 v121, 0x45800000, v0
	v_cndmask_b32_e32 v121, v0, v121, vcc
	v_exp_f32_e32 v130, v130
	s_waitcnt vmcnt(21)
	v_lshlrev_b32_e32 v0, 16, v178
	v_sub_f32_e32 v0, v0, v120
	v_mul_f32_e32 v0, v0, v121
	v_mul_f32_e32 v0, v151, v0
	v_mul_f32_e32 v0, v110, v0
	v_add_f32_e32 v130, 1.0, v130
	v_rcp_f32_e32 v130, v130
	v_cvt_pk_bf16_f32 v0, v0, s0
	v_mul_f32_e32 v106, v106, v130
	v_mul_f32_e32 v130, 0xbfb8aa3b, v102
	v_exp_f32_e32 v130, v130
	s_waitcnt vmcnt(20)
	v_lshlrev_b32_e32 v110, 16, v179
	v_sub_f32_e32 v110, v110, v120
	v_mul_f32_e32 v110, v110, v121
	v_mul_f32_e32 v110, v150, v110
	v_mul_f32_e32 v106, v106, v110
	v_add_f32_e32 v130, 1.0, v130
	v_rcp_f32_e32 v130, v130
	v_cvt_pk_bf16_f32 v106, v106, s0
	v_mul_f32_e32 v102, v102, v130
	s_waitcnt vmcnt(19)
	v_lshlrev_b32_e32 v110, 16, v180
	v_sub_f32_e32 v110, v110, v120
	v_mul_f32_e32 v110, v110, v121
	v_mul_f32_e32 v110, v149, v110
	v_mul_f32_e32 v102, v102, v110
	v_cvt_pk_bf16_f32 v102, v102, s0
	s_waitcnt vmcnt(18)
	v_lshlrev_b32_e32 v110, 16, v181
	v_sub_f32_e32 v110, v110, v120
	v_mul_f32_e32 v120, 0xbfb8aa3b, v98
	v_exp_f32_e32 v120, v120
	s_waitcnt vmcnt(16)
; __device__ __forceinline__ float bf2f(u16 b) { return __uint_as_float(((unsigned)b) << 16); }
; __device__ __forceinline__ float silu_f(float g) { return g * __builtin_amdgcn_rcpf(1.f + __builtin_amdgcn_exp2f(-g * LOG2E)); }
; template <int EPI>
; __device__ __forceinline__ void epilogue(const Params& p, int pass, int layer, int pm, int pn,
;                                          f32x4 (&acc)[2][2][4][2], const float* xin, float* xout) {
;     ...
;         for (int j = 0; j < 4; ++j) {
;           float s1 = s01[j].x + s01[j].z + s23[j].x + s23[j].z, s2 = s01[j].y + s01[j].w + s23[j].y + s23[j].w;
;           float mu = s1 * (1.f / 512.f);
;           float var = s2 * (1.f / 512.f) - mu * mu;
;           float rstd = rsqrtf(fmaxf(var, 0.f) + 1e-5f);
; #pragma unroll
;           for (int bj = 0; bj < 2; ++bj)
; #pragma unroll
;             for (int n = 0; n < 2; ++n) {
;               float g = acc[ai][bj][m][n][j];
;               float yn = (bf2f(yv[j][bj][n]) - mu) * rstd * gn[bj][n];
;               Y[(long)(tb + j) * YS + pn * 256 + bj * 128 + wc * 32 + n * 16 + fr] = f2bf(silu_f(g) * yn);
;             }
	v_pk_add_f32 v[116:117], v[198:199], v[200:201]
	v_mul_f32_e32 v110, v110, v121
	v_pk_add_f32 v[116:117], v[116:117], v[194:195]
	v_add_f32_e32 v120, 1.0, v120
	v_rcp_f32_e32 v120, v120
	v_mul_f32_e32 v110, v148, v110
	v_pk_add_f32 v[116:117], v[116:117], v[196:197]
	v_mul_f32_e32 v98, v98, v120
	v_mul_f32_e32 v98, v98, v110
	v_pk_mul_f32 v[116:117], v[116:117], s[18:19] op_sel_hi:[1,0]
	v_cvt_pk_bf16_f32 v110, v98, s0
	v_fma_f32 v98, -v116, v116, v117
	v_max_f32_e32 v98, 0, v98
	v_add_f32_e32 v98, 0x3727c5ac, v98
	v_cmp_gt_f32_e32 vcc, s25, v98
	v_mul_f32_e32 v117, 0x4b800000, v98
	v_mul_f32_e32 v120, 0xbfb8aa3b, v111
	v_cndmask_b32_e32 v98, v98, v117, vcc
	v_rsq_f32_e32 v98, v98
	v_exp_f32_e32 v120, v120
	v_mul_f32_e32 v117, 0x45800000, v98
	v_cndmask_b32_e32 v98, v98, v117, vcc
	v_add_f32_e32 v120, 1.0, v120
	v_rcp_f32_e32 v120, v120
	s_waitcnt vmcnt(15)
	v_lshlrev_b32_e32 v117, 16, v182
	v_sub_f32_e32 v117, v117, v116
	v_mul_f32_e32 v117, v117, v98
	v_mul_f32_e32 v117, v151, v117
	v_mul_f32_e32 v111, v111, v120
	v_mul_f32_e32 v111, v111, v117
	v_mul_f32_e32 v120, 0xbfb8aa3b, v107
	v_exp_f32_e32 v120, v120
	v_cvt_pk_bf16_f32 v111, v111, s0
	v_add_f32_e32 v120, 1.0, v120
	v_rcp_f32_e32 v120, v120
	s_waitcnt vmcnt(14)
	v_lshlrev_b32_e32 v117, 16, v183
	v_sub_f32_e32 v117, v117, v116
	v_mul_f32_e32 v117, v117, v98
	v_mul_f32_e32 v117, v150, v117
	v_mul_f32_e32 v107, v107, v120
	v_mul_f32_e32 v107, v107, v117
	v_mul_f32_e32 v120, 0xbfb8aa3b, v103
	v_exp_f32_e32 v120, v120
	v_cvt_pk_bf16_f32 v107, v107, s0
	v_add_f32_e32 v120, 1.0, v120
	v_rcp_f32_e32 v120, v120
	s_waitcnt vmcnt(13)
	v_lshlrev_b32_e32 v117, 16, v184
	v_sub_f32_e32 v117, v117, v116
	v_mul_f32_e32 v117, v117, v98
	v_mul_f32_e32 v117, v149, v117
	v_mul_f32_e32 v103, v103, v120
	v_mul_f32_e32 v103, v103, v117
	v_cvt_pk_bf16_f32 v103, v103, s0
	s_waitcnt vmcnt(12)
	v_lshlrev_b32_e32 v117, 16, v185
	v_sub_f32_e32 v116, v117, v116
	v_mul_f32_e32 v98, v116, v98
	v_mul_f32_e32 v116, 0xbfb8aa3b, v99
	v_exp_f32_e32 v116, v116
	v_mul_f32_e32 v98, v148, v98
	v_add_f32_e32 v116, 1.0, v116
	v_rcp_f32_e32 v116, v116
	s_nop 0
	v_mul_f32_e32 v99, v99, v116
	s_nop 0
	v_mul_f32_e32 v98, v99, v98
	v_cvt_pk_bf16_f32 v130, v98, s0
	s_waitcnt vmcnt(10)
	v_pk_add_f32 v[98:99], v[206:207], v[208:209]
	s_nop 0
	v_pk_add_f32 v[98:99], v[98:99], v[202:203]
	v_mul_f32_e32 v115, 0xbfb8aa3b, v112
	v_pk_add_f32 v[98:99], v[98:99], v[204:205]
	v_exp_f32_e32 v115, v115
	v_pk_mul_f32 v[98:99], v[98:99], s[18:19] op_sel_hi:[1,0]
	v_add_f32_e32 v115, 1.0, v115
	v_fma_f32 v99, -v98, v98, v99
	v_max_f32_e32 v99, 0, v99
	v_add_f32_e32 v99, 0x3727c5ac, v99
	v_cmp_gt_f32_e32 vcc, s25, v99
	v_mul_f32_e32 v114, 0x4b800000, v99
	v_rcp_f32_e32 v115, v115
	v_cndmask_b32_e32 v99, v99, v114, vcc
	v_rsq_f32_e32 v99, v99
	v_mul_f32_e32 v112, v112, v115
	v_mul_f32_e32 v115, 0xbfb8aa3b, v108
	v_mul_f32_e32 v114, 0x45800000, v99
	v_cndmask_b32_e32 v114, v99, v114, vcc
	v_exp_f32_e32 v115, v115
	s_waitcnt vmcnt(9)
	v_lshlrev_b32_e32 v99, 16, v186
	v_sub_f32_e32 v99, v99, v98
	v_mul_f32_e32 v99, v99, v114
	v_mul_f32_e32 v99, v151, v99
	v_mul_f32_e32 v99, v112, v99
	v_add_f32_e32 v115, 1.0, v115
	v_rcp_f32_e32 v115, v115
	v_cvt_pk_bf16_f32 v99, v99, s0
	v_mul_f32_e32 v108, v108, v115
	v_mul_f32_e32 v115, 0xbfb8aa3b, v104
	v_exp_f32_e32 v115, v115
	s_waitcnt vmcnt(8)
	v_lshlrev_b32_e32 v112, 16, v187
	v_sub_f32_e32 v112, v112, v98
	v_mul_f32_e32 v112, v112, v114
	v_mul_f32_e32 v112, v150, v112
	v_mul_f32_e32 v108, v108, v112
	v_add_f32_e32 v115, 1.0, v115
	v_rcp_f32_e32 v115, v115
	v_cvt_pk_bf16_f32 v108, v108, s0
	v_mul_f32_e32 v104, v104, v115
	s_waitcnt vmcnt(7)
	v_lshlrev_b32_e32 v112, 16, v188
	v_sub_f32_e32 v112, v112, v98
	v_mul_f32_e32 v112, v112, v114
	v_mul_f32_e32 v112, v149, v112
	v_mul_f32_e32 v104, v104, v112
	v_cvt_pk_bf16_f32 v104, v104, s0
	s_waitcnt vmcnt(6)
	v_lshlrev_b32_e32 v112, 16, v189
	v_sub_f32_e32 v98, v112, v98
	v_mul_f32_e32 v112, 0xbfb8aa3b, v100
	v_exp_f32_e32 v112, v112
	v_mul_f32_e32 v98, v98, v114
	v_mul_f32_e32 v98, v148, v98
	v_add_f32_e32 v112, 1.0, v112
	v_rcp_f32_e32 v112, v112
	s_nop 0
	v_mul_f32_e32 v100, v100, v112
	v_mul_f32_e32 v98, v100, v98
	s_nop 0
	s_nop 0
	v_cvt_pk_bf16_f32 v98, v98, s0
	global_store_short v[124:125], v0, off
	global_store_short v[124:125], v106, off offset:32
	global_store_short v[124:125], v102, off offset:256
	global_store_short v[124:125], v110, off offset:288
	global_store_short v[126:127], v111, off
	global_store_short v[126:127], v107, off offset:32
	global_store_short v[126:127], v103, off offset:256
	global_store_short v[126:127], v130, off offset:288
	global_store_short v[128:129], v99, off
	global_store_short v[128:129], v108, off offset:32
	global_store_short v[128:129], v104, off offset:256
	global_store_short v[128:129], v98, off offset:288
	v_or_b32_e32 v102, 32, v152
	s_waitcnt vmcnt(16)
	v_pk_add_f32 v[98:99], v[214:215], v[216:217]
	s_nop 0
	v_pk_add_f32 v[98:99], v[98:99], v[210:211]
	s_nop 0
	v_pk_add_f32 v[98:99], v[98:99], v[212:213]
	s_nop 0
	v_pk_mul_f32 v[98:99], v[98:99], s[18:19] op_sel_hi:[1,0]
	s_nop 0
	v_fma_f32 v0, -v98, v98, v99
	v_max_f32_e32 v0, 0, v0
	v_add_f32_e32 v0, 0x3727c5ac, v0
	v_cmp_gt_f32_e32 vcc, s25, v0
	v_mul_f32_e32 v99, 0x4b800000, v0
	s_nop 0
	v_cndmask_b32_e32 v0, v0, v99, vcc
	v_rsq_f32_e32 v0, v0
	s_nop 0
	v_mul_f32_e32 v99, 0x45800000, v0
	v_cndmask_b32_e32 v0, v0, v99, vcc
	s_waitcnt vmcnt(15)
; __device__ __forceinline__ float bf2f(u16 b) { return __uint_as_float(((unsigned)b) << 16); }
; __device__ __forceinline__ float silu_f(float g) { return g * __builtin_amdgcn_rcpf(1.f + __builtin_amdgcn_exp2f(-g * LOG2E)); }
; template <int EPI>
; __device__ __forceinline__ void epilogue(const Params& p, int pass, int layer, int pm, int pn,
;                                          f32x4 (&acc)[2][2][4][2], const float* xin, float* xout) {
;     ...
;         int tb = t0 + ai * 128 + wr * 64 + m * 16 + fq * 4;
;         asm volatile("" : "+v"(tb));
;         float4 s01[4], s23[4];
;         u16 yv[4][2][2];
; #pragma unroll
;         for (int j = 0; j < 4; ++j) {
;           const float4* sp = (const float4*)(stat + ((long)(tb + j) * 8 + h) * 8);
;           s01[j] = sp[0]; s23[j] = sp[1];
; #pragma unroll
;           for (int bj = 0; bj < 2; ++bj)
; #pragma unroll
;             for (int n = 0; n < 2; ++n)
;               yv[j][bj][n] = Y[(long)(tb + j) * YS + pn * 256 + bj * 128 + wc * 32 + n * 16 + fr];
;         }
; #pragma unroll
;         for (int j = 0; j < 4; ++j) {
;           float s1 = s01[j].x + s01[j].z + s23[j].x + s23[j].z, s2 = s01[j].y + s01[j].w + s23[j].y + s23[j].w;
;           float mu = s1 * (1.f / 512.f);
;           float var = s2 * (1.f / 512.f) - mu * mu;
;           float rstd = rsqrtf(fmaxf(var, 0.f) + 1e-5f);
; #pragma unroll
;           for (int bj = 0; bj < 2; ++bj)
; #pragma unroll
;             for (int n = 0; n < 2; ++n) {
;               float g = acc[ai][bj][m][n][j];
;               float yn = (bf2f(yv[j][bj][n]) - mu) * rstd * gn[bj][n];
;               Y[(long)(tb + j) * YS + pn * 256 + bj * 128 + wc * 32 + n * 16 + fr] = f2bf(silu_f(g) * yn);
;             }
	v_lshlrev_b32_e32 v99, 16, v190
	v_mul_f32_e32 v100, 0xbfb8aa3b, v113
	v_exp_f32_e32 v100, v100
	v_sub_f32_e32 v99, v99, v98
	v_mul_f32_e32 v99, v99, v0
	v_mul_f32_e32 v99, v151, v99
	v_add_f32_e32 v100, 1.0, v100
	v_rcp_f32_e32 v100, v100
	s_nop 0
	v_mul_f32_e32 v100, v113, v100
	v_mul_f32_e32 v99, v100, v99
	v_mul_f32_e32 v100, 0xbfb8aa3b, v109
	v_exp_f32_e32 v100, v100
	v_cvt_pk_bf16_f32 v99, v99, s0
	global_store_short v[122:123], v99, off
	s_waitcnt vmcnt(15)
	v_lshlrev_b32_e32 v99, 16, v191
	v_add_f32_e32 v100, 1.0, v100
	v_rcp_f32_e32 v100, v100
	v_sub_f32_e32 v99, v99, v98
	v_mul_f32_e32 v99, v99, v0
	v_mul_f32_e32 v99, v150, v99
	v_mul_f32_e32 v100, v109, v100
	v_mul_f32_e32 v99, v100, v99
	v_mul_f32_e32 v100, 0xbfb8aa3b, v105
	v_exp_f32_e32 v100, v100
	v_cvt_pk_bf16_f32 v99, v99, s0
	global_store_short v[122:123], v99, off offset:32
	s_waitcnt vmcnt(15)
	v_lshlrev_b32_e32 v99, 16, v192
	v_add_f32_e32 v100, 1.0, v100
	v_rcp_f32_e32 v100, v100
	v_sub_f32_e32 v99, v99, v98
	v_mul_f32_e32 v99, v99, v0
	v_mul_f32_e32 v99, v149, v99
	v_mul_f32_e32 v100, v105, v100
	v_mul_f32_e32 v99, v100, v99
	v_cvt_pk_bf16_f32 v99, v99, s0
	global_store_short v[122:123], v99, off offset:256
	s_waitcnt vmcnt(15)
	v_lshlrev_b32_e32 v99, 16, v193
	v_sub_f32_e32 v98, v99, v98
	v_mul_f32_e32 v0, v98, v0
	v_mul_f32_e32 v98, 0xbfb8aa3b, v101
	v_exp_f32_e32 v98, v98
	v_mul_f32_e32 v0, v148, v0
	v_add_f32_e32 v98, 1.0, v98
	v_rcp_f32_e32 v98, v98
	s_nop 0
	v_mul_f32_e32 v98, v101, v98
	v_mul_f32_e32 v0, v98, v0
	v_cvt_pk_bf16_f32 v0, v0, s0
	global_store_short v[122:123], v0, off offset:288
	s_nop 0
	v_ashrrev_i32_e32 v103, 31, v102
	v_lshlrev_b64 v[98:99], 8, v[102:103]
	v_lshl_add_u64 v[104:105], s[16:17], 0, v[98:99]
	global_load_dwordx4 v[114:117], v[104:105], off offset:16
	global_load_dwordx4 v[118:121], v[104:105], off
	v_mad_i64_i32 v[108:109], s[14:15], v102, s24, v[138:139]
	global_load_ushort v162, v[108:109], off
	global_load_ushort v163, v[108:109], off offset:32
	global_load_ushort v164, v[108:109], off offset:256
	global_load_ushort v165, v[108:109], off offset:288
	v_add_u32_e32 v98, 1, v102
	v_ashrrev_i32_e32 v99, 31, v98
	v_lshlrev_b64 v[100:101], 8, v[98:99]
	v_lshl_add_u64 v[100:101], s[16:17], 0, v[100:101]
	global_load_dwordx4 v[194:197], v[100:101], off offset:16
	global_load_dwordx4 v[198:201], v[100:101], off
	v_mad_i64_i32 v[110:111], s[14:15], v98, s24, v[138:139]
	global_load_ushort v166, v[110:111], off
	global_load_ushort v167, v[110:111], off offset:32
	global_load_ushort v168, v[110:111], off offset:256
	global_load_ushort v169, v[110:111], off offset:288
	v_add_u32_e32 v106, 2, v102
	v_ashrrev_i32_e32 v107, 31, v106
	v_lshlrev_b64 v[98:99], 8, v[106:107]
	v_lshl_add_u64 v[98:99], s[16:17], 0, v[98:99]
	global_load_dwordx4 v[202:205], v[98:99], off offset:16
	global_load_dwordx4 v[206:209], v[98:99], off
	v_mad_i64_i32 v[112:113], s[14:15], v106, s24, v[138:139]
	global_load_ushort v170, v[112:113], off
	global_load_ushort v171, v[112:113], off offset:32
	global_load_ushort v172, v[112:113], off offset:256
	global_load_ushort v173, v[112:113], off offset:288
	v_add_u32_e32 v106, 3, v102
	v_ashrrev_i32_e32 v107, 31, v106
	v_lshlrev_b64 v[102:103], 8, v[106:107]
	v_lshl_add_u64 v[102:103], s[16:17], 0, v[102:103]
	global_load_dwordx4 v[210:213], v[102:103], off offset:16
	global_load_dwordx4 v[214:217], v[102:103], off
	v_mad_i64_i32 v[106:107], s[14:15], v106, s24, v[138:139]
	global_load_ushort v174, v[106:107], off
	global_load_ushort v175, v[106:107], off offset:32
	global_load_ushort v176, v[106:107], off offset:256
	global_load_ushort v177, v[106:107], off offset:288
	s_waitcnt vmcnt(22)
	v_pk_add_f32 v[104:105], v[118:119], v[120:121]
	s_nop 0
	v_pk_add_f32 v[104:105], v[104:105], v[114:115]
	v_mul_f32_e32 v114, 0xbfb8aa3b, v94
	v_pk_add_f32 v[104:105], v[104:105], v[116:117]
	v_exp_f32_e32 v114, v114
	v_pk_mul_f32 v[104:105], v[104:105], s[18:19] op_sel_hi:[1,0]
	v_add_f32_e32 v114, 1.0, v114
	v_fma_f32 v0, -v104, v104, v105
	v_max_f32_e32 v0, 0, v0
	v_add_f32_e32 v0, 0x3727c5ac, v0
	v_cmp_gt_f32_e32 vcc, s25, v0
	v_mul_f32_e32 v105, 0x4b800000, v0
	v_rcp_f32_e32 v114, v114
	v_cndmask_b32_e32 v0, v0, v105, vcc
	v_rsq_f32_e32 v0, v0
	v_mul_f32_e32 v94, v94, v114
	v_mul_f32_e32 v114, 0xbfb8aa3b, v90
	v_mul_f32_e32 v105, 0x45800000, v0
	v_cndmask_b32_e32 v105, v0, v105, vcc
	v_exp_f32_e32 v114, v114
	s_waitcnt vmcnt(21)
	v_lshlrev_b32_e32 v0, 16, v162
	v_sub_f32_e32 v0, v0, v104
	v_mul_f32_e32 v0, v0, v105
	v_mul_f32_e32 v0, v151, v0
	v_mul_f32_e32 v0, v94, v0
	v_add_f32_e32 v114, 1.0, v114
	v_rcp_f32_e32 v114, v114
	v_cvt_pk_bf16_f32 v0, v0, s0
	v_mul_f32_e32 v90, v90, v114
	v_mul_f32_e32 v114, 0xbfb8aa3b, v86
	v_exp_f32_e32 v114, v114
	s_waitcnt vmcnt(20)
	v_lshlrev_b32_e32 v94, 16, v163
	v_sub_f32_e32 v94, v94, v104
	v_mul_f32_e32 v94, v94, v105
	v_mul_f32_e32 v94, v150, v94
	v_mul_f32_e32 v90, v90, v94
	v_add_f32_e32 v114, 1.0, v114
	v_rcp_f32_e32 v114, v114
	v_cvt_pk_bf16_f32 v90, v90, s0
	v_mul_f32_e32 v86, v86, v114
	s_waitcnt vmcnt(19)
	v_lshlrev_b32_e32 v94, 16, v164
	v_sub_f32_e32 v94, v94, v104
	v_mul_f32_e32 v94, v94, v105
	v_mul_f32_e32 v94, v149, v94
	v_mul_f32_e32 v86, v86, v94
	v_cvt_pk_bf16_f32 v86, v86, s0
	s_waitcnt vmcnt(18)
	v_lshlrev_b32_e32 v94, 16, v165
	v_sub_f32_e32 v94, v94, v104
	v_mul_f32_e32 v104, 0xbfb8aa3b, v82
	v_exp_f32_e32 v104, v104
	s_waitcnt vmcnt(16)
; __device__ __forceinline__ float bf2f(u16 b) { return __uint_as_float(((unsigned)b) << 16); }
; __device__ __forceinline__ float silu_f(float g) { return g * __builtin_amdgcn_rcpf(1.f + __builtin_amdgcn_exp2f(-g * LOG2E)); }
; template <int EPI>
; __device__ __forceinline__ void epilogue(const Params& p, int pass, int layer, int pm, int pn,
;                                          f32x4 (&acc)[2][2][4][2], const float* xin, float* xout) {
;     ...
;         for (int j = 0; j < 4; ++j) {
;           float s1 = s01[j].x + s01[j].z + s23[j].x + s23[j].z, s2 = s01[j].y + s01[j].w + s23[j].y + s23[j].w;
;           float mu = s1 * (1.f / 512.f);
;           float var = s2 * (1.f / 512.f) - mu * mu;
;           float rstd = rsqrtf(fmaxf(var, 0.f) + 1e-5f);
; #pragma unroll
;           for (int bj = 0; bj < 2; ++bj)
; #pragma unroll
;             for (int n = 0; n < 2; ++n) {
;               float g = acc[ai][bj][m][n][j];
;               float yn = (bf2f(yv[j][bj][n]) - mu) * rstd * gn[bj][n];
;               Y[(long)(tb + j) * YS + pn * 256 + bj * 128 + wc * 32 + n * 16 + fr] = f2bf(silu_f(g) * yn);
;             }
	v_pk_add_f32 v[100:101], v[198:199], v[200:201]
	v_mul_f32_e32 v94, v94, v105
	v_pk_add_f32 v[100:101], v[100:101], v[194:195]
	v_add_f32_e32 v104, 1.0, v104
	v_rcp_f32_e32 v104, v104
	v_mul_f32_e32 v94, v148, v94
	v_pk_add_f32 v[100:101], v[100:101], v[196:197]
	v_mul_f32_e32 v82, v82, v104
	v_mul_f32_e32 v82, v82, v94
	v_pk_mul_f32 v[100:101], v[100:101], s[18:19] op_sel_hi:[1,0]
	v_cvt_pk_bf16_f32 v94, v82, s0
	v_fma_f32 v82, -v100, v100, v101
	v_max_f32_e32 v82, 0, v82
	v_add_f32_e32 v82, 0x3727c5ac, v82
	v_cmp_gt_f32_e32 vcc, s25, v82
	v_mul_f32_e32 v101, 0x4b800000, v82
	v_mul_f32_e32 v104, 0xbfb8aa3b, v95
	v_cndmask_b32_e32 v82, v82, v101, vcc
	v_rsq_f32_e32 v82, v82
	v_exp_f32_e32 v104, v104
	v_mul_f32_e32 v101, 0x45800000, v82
	v_cndmask_b32_e32 v82, v82, v101, vcc
	v_add_f32_e32 v104, 1.0, v104
	v_rcp_f32_e32 v104, v104
	s_waitcnt vmcnt(15)
	v_lshlrev_b32_e32 v101, 16, v166
	v_sub_f32_e32 v101, v101, v100
	v_mul_f32_e32 v101, v101, v82
	v_mul_f32_e32 v101, v151, v101
	v_mul_f32_e32 v95, v95, v104
	v_mul_f32_e32 v95, v95, v101
	v_mul_f32_e32 v104, 0xbfb8aa3b, v91
	v_exp_f32_e32 v104, v104
	v_cvt_pk_bf16_f32 v95, v95, s0
	v_add_f32_e32 v104, 1.0, v104
	v_rcp_f32_e32 v104, v104
	s_waitcnt vmcnt(14)
	v_lshlrev_b32_e32 v101, 16, v167
	v_sub_f32_e32 v101, v101, v100
	v_mul_f32_e32 v101, v101, v82
	v_mul_f32_e32 v101, v150, v101
	v_mul_f32_e32 v91, v91, v104
	v_mul_f32_e32 v91, v91, v101
	v_mul_f32_e32 v104, 0xbfb8aa3b, v87
	v_exp_f32_e32 v104, v104
	v_cvt_pk_bf16_f32 v91, v91, s0
	v_add_f32_e32 v104, 1.0, v104
	v_rcp_f32_e32 v104, v104
	s_waitcnt vmcnt(13)
	v_lshlrev_b32_e32 v101, 16, v168
	v_sub_f32_e32 v101, v101, v100
	v_mul_f32_e32 v101, v101, v82
	v_mul_f32_e32 v101, v149, v101
	v_mul_f32_e32 v87, v87, v104
	v_mul_f32_e32 v87, v87, v101
	v_cvt_pk_bf16_f32 v87, v87, s0
	s_waitcnt vmcnt(12)
	v_lshlrev_b32_e32 v101, 16, v169
	v_sub_f32_e32 v100, v101, v100
	v_mul_f32_e32 v82, v100, v82
	v_mul_f32_e32 v100, 0xbfb8aa3b, v83
	v_exp_f32_e32 v100, v100
	v_mul_f32_e32 v82, v148, v82
	v_add_f32_e32 v100, 1.0, v100
	v_rcp_f32_e32 v100, v100
	s_nop 0
	v_mul_f32_e32 v83, v83, v100
	s_nop 0
	v_mul_f32_e32 v82, v83, v82
	v_cvt_pk_bf16_f32 v114, v82, s0
	s_waitcnt vmcnt(10)
	v_pk_add_f32 v[82:83], v[206:207], v[208:209]
	s_nop 0
	v_pk_add_f32 v[82:83], v[82:83], v[202:203]
	v_mul_f32_e32 v99, 0xbfb8aa3b, v96
	v_pk_add_f32 v[82:83], v[82:83], v[204:205]
	v_exp_f32_e32 v99, v99
	v_pk_mul_f32 v[82:83], v[82:83], s[18:19] op_sel_hi:[1,0]
	v_add_f32_e32 v99, 1.0, v99
	v_fma_f32 v83, -v82, v82, v83
	v_max_f32_e32 v83, 0, v83
	v_add_f32_e32 v83, 0x3727c5ac, v83
	v_cmp_gt_f32_e32 vcc, s25, v83
	v_mul_f32_e32 v98, 0x4b800000, v83
	v_rcp_f32_e32 v99, v99
	v_cndmask_b32_e32 v83, v83, v98, vcc
	v_rsq_f32_e32 v83, v83
	v_mul_f32_e32 v96, v96, v99
	v_mul_f32_e32 v99, 0xbfb8aa3b, v92
	v_mul_f32_e32 v98, 0x45800000, v83
	v_cndmask_b32_e32 v98, v83, v98, vcc
	v_exp_f32_e32 v99, v99
	s_waitcnt vmcnt(9)
	v_lshlrev_b32_e32 v83, 16, v170
	v_sub_f32_e32 v83, v83, v82
	v_mul_f32_e32 v83, v83, v98
	v_mul_f32_e32 v83, v151, v83
	v_mul_f32_e32 v83, v96, v83
	v_add_f32_e32 v99, 1.0, v99
	v_rcp_f32_e32 v99, v99
	v_cvt_pk_bf16_f32 v83, v83, s0
	v_mul_f32_e32 v92, v92, v99
	v_mul_f32_e32 v99, 0xbfb8aa3b, v88
	v_exp_f32_e32 v99, v99
	s_waitcnt vmcnt(8)
	v_lshlrev_b32_e32 v96, 16, v171
	v_sub_f32_e32 v96, v96, v82
	v_mul_f32_e32 v96, v96, v98
	v_mul_f32_e32 v96, v150, v96
	v_mul_f32_e32 v92, v92, v96
	v_add_f32_e32 v99, 1.0, v99
	v_rcp_f32_e32 v99, v99
	v_cvt_pk_bf16_f32 v92, v92, s0
	v_mul_f32_e32 v88, v88, v99
	s_waitcnt vmcnt(7)
	v_lshlrev_b32_e32 v96, 16, v172
	v_sub_f32_e32 v96, v96, v82
	v_mul_f32_e32 v96, v96, v98
	v_mul_f32_e32 v96, v149, v96
	v_mul_f32_e32 v88, v88, v96
	v_cvt_pk_bf16_f32 v88, v88, s0
	s_waitcnt vmcnt(6)
	v_lshlrev_b32_e32 v96, 16, v173
	v_sub_f32_e32 v82, v96, v82
	v_mul_f32_e32 v96, 0xbfb8aa3b, v84
	v_exp_f32_e32 v96, v96
	v_mul_f32_e32 v82, v82, v98
	v_mul_f32_e32 v82, v148, v82
	v_add_f32_e32 v96, 1.0, v96
	v_rcp_f32_e32 v96, v96
	s_nop 0
	v_mul_f32_e32 v84, v84, v96
	v_mul_f32_e32 v82, v84, v82
	s_nop 0
	s_nop 0
	v_cvt_pk_bf16_f32 v82, v82, s0
	global_store_short v[108:109], v0, off
	global_store_short v[108:109], v90, off offset:32
	global_store_short v[108:109], v86, off offset:256
	global_store_short v[108:109], v94, off offset:288
	global_store_short v[110:111], v95, off
	global_store_short v[110:111], v91, off offset:32
	global_store_short v[110:111], v87, off offset:256
	global_store_short v[110:111], v114, off offset:288
	global_store_short v[112:113], v83, off
	global_store_short v[112:113], v92, off offset:32
	global_store_short v[112:113], v88, off offset:256
	global_store_short v[112:113], v82, off offset:288
	v_or_b32_e32 v86, 48, v152
	s_waitcnt vmcnt(16)
	v_pk_add_f32 v[82:83], v[214:215], v[216:217]
	s_nop 0
	v_pk_add_f32 v[82:83], v[82:83], v[210:211]
	s_nop 0
	v_pk_add_f32 v[82:83], v[82:83], v[212:213]
	s_nop 0
	v_pk_mul_f32 v[82:83], v[82:83], s[18:19] op_sel_hi:[1,0]
	s_nop 0
	v_fma_f32 v0, -v82, v82, v83
	v_max_f32_e32 v0, 0, v0
	v_add_f32_e32 v0, 0x3727c5ac, v0
	v_cmp_gt_f32_e32 vcc, s25, v0
	v_mul_f32_e32 v83, 0x4b800000, v0
	s_nop 0
	v_cndmask_b32_e32 v0, v0, v83, vcc
	v_rsq_f32_e32 v0, v0
	s_nop 0
	v_mul_f32_e32 v83, 0x45800000, v0
	v_cndmask_b32_e32 v0, v0, v83, vcc
	s_waitcnt vmcnt(15)
	v_lshlrev_b32_e32 v83, 16, v174
	v_mul_f32_e32 v84, 0xbfb8aa3b, v97
	v_exp_f32_e32 v84, v84
	v_sub_f32_e32 v83, v83, v82
	v_mul_f32_e32 v83, v83, v0
	v_mul_f32_e32 v83, v151, v83
	v_add_f32_e32 v84, 1.0, v84
	v_rcp_f32_e32 v84, v84
	s_nop 0
	v_mul_f32_e32 v84, v97, v84
	v_mul_f32_e32 v83, v84, v83
	v_mul_f32_e32 v84, 0xbfb8aa3b, v93
	v_exp_f32_e32 v84, v84
	v_cvt_pk_bf16_f32 v83, v83, s0
	global_store_short v[106:107], v83, off
	s_waitcnt vmcnt(15)
; __device__ __forceinline__ float bf2f(u16 b) { return __uint_as_float(((unsigned)b) << 16); }
; __device__ __forceinline__ float silu_f(float g) { return g * __builtin_amdgcn_rcpf(1.f + __builtin_amdgcn_exp2f(-g * LOG2E)); }
; template <int EPI>
; __device__ __forceinline__ void epilogue(const Params& p, int pass, int layer, int pm, int pn,
;                                          f32x4 (&acc)[2][2][4][2], const float* xin, float* xout) {
;     ...
;         int tb = t0 + ai * 128 + wr * 64 + m * 16 + fq * 4;
;         asm volatile("" : "+v"(tb));
;         float4 s01[4], s23[4];
;         u16 yv[4][2][2];
; #pragma unroll
;         for (int j = 0; j < 4; ++j) {
;           const float4* sp = (const float4*)(stat + ((long)(tb + j) * 8 + h) * 8);
;           s01[j] = sp[0]; s23[j] = sp[1];
; #pragma unroll
;           for (int bj = 0; bj < 2; ++bj)
; #pragma unroll
;             for (int n = 0; n < 2; ++n)
;               yv[j][bj][n] = Y[(long)(tb + j) * YS + pn * 256 + bj * 128 + wc * 32 + n * 16 + fr];
;         }
; #pragma unroll
;         for (int j = 0; j < 4; ++j) {
;           float s1 = s01[j].x + s01[j].z + s23[j].x + s23[j].z, s2 = s01[j].y + s01[j].w + s23[j].y + s23[j].w;
;           float mu = s1 * (1.f / 512.f);
;           float var = s2 * (1.f / 512.f) - mu * mu;
;           float rstd = rsqrtf(fmaxf(var, 0.f) + 1e-5f);
; #pragma unroll
;           for (int bj = 0; bj < 2; ++bj)
; #pragma unroll
;             for (int n = 0; n < 2; ++n) {
;               float g = acc[ai][bj][m][n][j];
;               float yn = (bf2f(yv[j][bj][n]) - mu) * rstd * gn[bj][n];
;               Y[(long)(tb + j) * YS + pn * 256 + bj * 128 + wc * 32 + n * 16 + fr] = f2bf(silu_f(g) * yn);
;             }
	v_lshlrev_b32_e32 v83, 16, v175
	v_add_f32_e32 v84, 1.0, v84
	v_rcp_f32_e32 v84, v84
	v_sub_f32_e32 v83, v83, v82
	v_mul_f32_e32 v83, v83, v0
	v_mul_f32_e32 v83, v150, v83
	v_mul_f32_e32 v84, v93, v84
	v_mul_f32_e32 v83, v84, v83
	v_mul_f32_e32 v84, 0xbfb8aa3b, v89
	v_exp_f32_e32 v84, v84
	v_cvt_pk_bf16_f32 v83, v83, s0
	global_store_short v[106:107], v83, off offset:32
	s_waitcnt vmcnt(15)
	v_lshlrev_b32_e32 v83, 16, v176
	v_add_f32_e32 v84, 1.0, v84
	v_rcp_f32_e32 v84, v84
	v_sub_f32_e32 v83, v83, v82
	v_mul_f32_e32 v83, v83, v0
	v_mul_f32_e32 v83, v149, v83
	v_mul_f32_e32 v84, v89, v84
	v_mul_f32_e32 v83, v84, v83
	v_cvt_pk_bf16_f32 v83, v83, s0
	global_store_short v[106:107], v83, off offset:256
	s_waitcnt vmcnt(15)
	v_lshlrev_b32_e32 v83, 16, v177
	v_sub_f32_e32 v82, v83, v82
	v_mul_f32_e32 v0, v82, v0
	v_mul_f32_e32 v82, 0xbfb8aa3b, v85
	v_exp_f32_e32 v82, v82
	v_mul_f32_e32 v0, v148, v0
	v_add_f32_e32 v82, 1.0, v82
	v_rcp_f32_e32 v82, v82
	s_nop 0
	v_mul_f32_e32 v82, v85, v82
	v_mul_f32_e32 v0, v82, v0
	v_cvt_pk_bf16_f32 v0, v0, s0
	global_store_short v[106:107], v0, off offset:288
	s_nop 0
	v_ashrrev_i32_e32 v87, 31, v86
	v_lshlrev_b64 v[82:83], 8, v[86:87]
	v_lshl_add_u64 v[88:89], s[16:17], 0, v[82:83]
	global_load_dwordx4 v[98:101], v[88:89], off offset:16
	global_load_dwordx4 v[102:105], v[88:89], off
	v_mad_i64_i32 v[92:93], s[14:15], v86, s24, v[138:139]
	global_load_ushort v178, v[92:93], off
	global_load_ushort v179, v[92:93], off offset:32
	global_load_ushort v180, v[92:93], off offset:256
	global_load_ushort v181, v[92:93], off offset:288
	v_add_u32_e32 v82, 1, v86
	v_ashrrev_i32_e32 v83, 31, v82
	v_lshlrev_b64 v[84:85], 8, v[82:83]
	v_lshl_add_u64 v[84:85], s[16:17], 0, v[84:85]
	global_load_dwordx4 v[194:197], v[84:85], off offset:16
	global_load_dwordx4 v[198:201], v[84:85], off
	v_mad_i64_i32 v[94:95], s[14:15], v82, s24, v[138:139]
	global_load_ushort v182, v[94:95], off
	global_load_ushort v183, v[94:95], off offset:32
	global_load_ushort v184, v[94:95], off offset:256
	global_load_ushort v185, v[94:95], off offset:288
	v_add_u32_e32 v90, 2, v86
	v_ashrrev_i32_e32 v91, 31, v90
	v_lshlrev_b64 v[82:83], 8, v[90:91]
	v_lshl_add_u64 v[82:83], s[16:17], 0, v[82:83]
	global_load_dwordx4 v[202:205], v[82:83], off offset:16
	global_load_dwordx4 v[206:209], v[82:83], off
	v_mad_i64_i32 v[96:97], s[14:15], v90, s24, v[138:139]
	global_load_ushort v186, v[96:97], off
	global_load_ushort v187, v[96:97], off offset:32
	global_load_ushort v188, v[96:97], off offset:256
	global_load_ushort v189, v[96:97], off offset:288
	v_add_u32_e32 v90, 3, v86
	v_ashrrev_i32_e32 v91, 31, v90
	v_lshlrev_b64 v[86:87], 8, v[90:91]
	v_lshl_add_u64 v[86:87], s[16:17], 0, v[86:87]
	global_load_dwordx4 v[210:213], v[86:87], off offset:16
	global_load_dwordx4 v[214:217], v[86:87], off
	v_mad_i64_i32 v[90:91], s[14:15], v90, s24, v[138:139]
	global_load_ushort v190, v[90:91], off
	global_load_ushort v191, v[90:91], off offset:32
	global_load_ushort v192, v[90:91], off offset:256
	global_load_ushort v193, v[90:91], off offset:288
	s_waitcnt vmcnt(22)
	v_pk_add_f32 v[88:89], v[102:103], v[104:105]
	s_nop 0
	v_pk_add_f32 v[88:89], v[88:89], v[98:99]
	v_mul_f32_e32 v98, 0xbfb8aa3b, v78
	v_pk_add_f32 v[88:89], v[88:89], v[100:101]
	v_exp_f32_e32 v98, v98
	v_pk_mul_f32 v[88:89], v[88:89], s[18:19] op_sel_hi:[1,0]
	v_add_f32_e32 v98, 1.0, v98
	v_fma_f32 v0, -v88, v88, v89
	v_max_f32_e32 v0, 0, v0
	v_add_f32_e32 v0, 0x3727c5ac, v0
	v_cmp_gt_f32_e32 vcc, s25, v0
	v_mul_f32_e32 v89, 0x4b800000, v0
	v_rcp_f32_e32 v98, v98
	v_cndmask_b32_e32 v0, v0, v89, vcc
	v_rsq_f32_e32 v0, v0
	v_mul_f32_e32 v78, v78, v98
	v_mul_f32_e32 v98, 0xbfb8aa3b, v74
	v_mul_f32_e32 v89, 0x45800000, v0
	v_cndmask_b32_e32 v89, v0, v89, vcc
	v_exp_f32_e32 v98, v98
	s_waitcnt vmcnt(21)
	v_lshlrev_b32_e32 v0, 16, v178
	v_sub_f32_e32 v0, v0, v88
	v_mul_f32_e32 v0, v0, v89
	v_mul_f32_e32 v0, v151, v0
	v_mul_f32_e32 v0, v78, v0
	v_add_f32_e32 v98, 1.0, v98
	v_rcp_f32_e32 v98, v98
	v_cvt_pk_bf16_f32 v0, v0, s0
	v_mul_f32_e32 v74, v74, v98
	v_mul_f32_e32 v98, 0xbfb8aa3b, v70
	v_exp_f32_e32 v98, v98
	s_waitcnt vmcnt(20)
	v_lshlrev_b32_e32 v78, 16, v179
	v_sub_f32_e32 v78, v78, v88
	v_mul_f32_e32 v78, v78, v89
	v_mul_f32_e32 v78, v150, v78
	v_mul_f32_e32 v74, v74, v78
	v_add_f32_e32 v98, 1.0, v98
	v_rcp_f32_e32 v98, v98
	v_cvt_pk_bf16_f32 v74, v74, s0
	v_mul_f32_e32 v70, v70, v98
	s_waitcnt vmcnt(19)
	v_lshlrev_b32_e32 v78, 16, v180
	v_sub_f32_e32 v78, v78, v88
	v_mul_f32_e32 v78, v78, v89
	v_mul_f32_e32 v78, v149, v78
	v_mul_f32_e32 v70, v70, v78
	v_cvt_pk_bf16_f32 v70, v70, s0
	s_waitcnt vmcnt(18)
	v_lshlrev_b32_e32 v78, 16, v181
	v_sub_f32_e32 v78, v78, v88
	v_mul_f32_e32 v88, 0xbfb8aa3b, v66
	v_exp_f32_e32 v88, v88
	s_waitcnt vmcnt(16)
	v_pk_add_f32 v[84:85], v[198:199], v[200:201]
	v_mul_f32_e32 v78, v78, v89
	v_pk_add_f32 v[84:85], v[84:85], v[194:195]
	v_add_f32_e32 v88, 1.0, v88
	v_rcp_f32_e32 v88, v88
	v_mul_f32_e32 v78, v148, v78
	v_pk_add_f32 v[84:85], v[84:85], v[196:197]
	v_mul_f32_e32 v66, v66, v88
	v_mul_f32_e32 v66, v66, v78
	v_pk_mul_f32 v[84:85], v[84:85], s[18:19] op_sel_hi:[1,0]
	v_cvt_pk_bf16_f32 v78, v66, s0
	v_fma_f32 v66, -v84, v84, v85
	v_max_f32_e32 v66, 0, v66
	v_add_f32_e32 v66, 0x3727c5ac, v66
	v_cmp_gt_f32_e32 vcc, s25, v66
	v_mul_f32_e32 v85, 0x4b800000, v66
	v_mul_f32_e32 v88, 0xbfb8aa3b, v79
	v_cndmask_b32_e32 v66, v66, v85, vcc
	v_rsq_f32_e32 v66, v66
	v_exp_f32_e32 v88, v88
	v_mul_f32_e32 v85, 0x45800000, v66
	v_cndmask_b32_e32 v66, v66, v85, vcc
	v_add_f32_e32 v88, 1.0, v88
	v_rcp_f32_e32 v88, v88
	s_waitcnt vmcnt(15)
; __device__ __forceinline__ float bf2f(u16 b) { return __uint_as_float(((unsigned)b) << 16); }
; __device__ __forceinline__ float silu_f(float g) { return g * __builtin_amdgcn_rcpf(1.f + __builtin_amdgcn_exp2f(-g * LOG2E)); }
; template <int EPI>
; __device__ __forceinline__ void epilogue(const Params& p, int pass, int layer, int pm, int pn,
;                                          f32x4 (&acc)[2][2][4][2], const float* xin, float* xout) {
;     ...
;         for (int j = 0; j < 4; ++j) {
;           float s1 = s01[j].x + s01[j].z + s23[j].x + s23[j].z, s2 = s01[j].y + s01[j].w + s23[j].y + s23[j].w;
;           float mu = s1 * (1.f / 512.f);
;           float var = s2 * (1.f / 512.f) - mu * mu;
;           float rstd = rsqrtf(fmaxf(var, 0.f) + 1e-5f);
; #pragma unroll
;           for (int bj = 0; bj < 2; ++bj)
; #pragma unroll
;             for (int n = 0; n < 2; ++n) {
;               float g = acc[ai][bj][m][n][j];
;               float yn = (bf2f(yv[j][bj][n]) - mu) * rstd * gn[bj][n];
;               Y[(long)(tb + j) * YS + pn * 256 + bj * 128 + wc * 32 + n * 16 + fr] = f2bf(silu_f(g) * yn);
;             }
	v_lshlrev_b32_e32 v85, 16, v182
	v_sub_f32_e32 v85, v85, v84
	v_mul_f32_e32 v85, v85, v66
	v_mul_f32_e32 v85, v151, v85
	v_mul_f32_e32 v79, v79, v88
	v_mul_f32_e32 v79, v79, v85
	v_mul_f32_e32 v88, 0xbfb8aa3b, v75
	v_exp_f32_e32 v88, v88
	v_cvt_pk_bf16_f32 v79, v79, s0
	v_add_f32_e32 v88, 1.0, v88
	v_rcp_f32_e32 v88, v88
	s_waitcnt vmcnt(14)
	v_lshlrev_b32_e32 v85, 16, v183
	v_sub_f32_e32 v85, v85, v84
	v_mul_f32_e32 v85, v85, v66
	v_mul_f32_e32 v85, v150, v85
	v_mul_f32_e32 v75, v75, v88
	v_mul_f32_e32 v75, v75, v85
	v_mul_f32_e32 v88, 0xbfb8aa3b, v71
	v_exp_f32_e32 v88, v88
	v_cvt_pk_bf16_f32 v75, v75, s0
	v_add_f32_e32 v88, 1.0, v88
	v_rcp_f32_e32 v88, v88
	s_waitcnt vmcnt(13)
	v_lshlrev_b32_e32 v85, 16, v184
	v_sub_f32_e32 v85, v85, v84
	v_mul_f32_e32 v85, v85, v66
	v_mul_f32_e32 v85, v149, v85
	v_mul_f32_e32 v71, v71, v88
	v_mul_f32_e32 v71, v71, v85
	v_cvt_pk_bf16_f32 v71, v71, s0
	s_waitcnt vmcnt(12)
	v_lshlrev_b32_e32 v85, 16, v185
	v_sub_f32_e32 v84, v85, v84
	v_mul_f32_e32 v66, v84, v66
	v_mul_f32_e32 v84, 0xbfb8aa3b, v67
	v_exp_f32_e32 v84, v84
	v_mul_f32_e32 v66, v148, v66
	v_add_f32_e32 v84, 1.0, v84
	v_rcp_f32_e32 v84, v84
	s_nop 0
	v_mul_f32_e32 v67, v67, v84
	s_nop 0
	v_mul_f32_e32 v66, v67, v66
	v_cvt_pk_bf16_f32 v98, v66, s0
	s_waitcnt vmcnt(10)
	v_pk_add_f32 v[66:67], v[206:207], v[208:209]
	s_nop 0
	v_pk_add_f32 v[66:67], v[66:67], v[202:203]
	v_mul_f32_e32 v83, 0xbfb8aa3b, v80
	v_pk_add_f32 v[66:67], v[66:67], v[204:205]
	v_exp_f32_e32 v83, v83
	v_pk_mul_f32 v[66:67], v[66:67], s[18:19] op_sel_hi:[1,0]
	v_add_f32_e32 v83, 1.0, v83
	v_fma_f32 v67, -v66, v66, v67
	v_max_f32_e32 v67, 0, v67
	v_add_f32_e32 v67, 0x3727c5ac, v67
	v_cmp_gt_f32_e32 vcc, s25, v67
	v_mul_f32_e32 v82, 0x4b800000, v67
	v_rcp_f32_e32 v83, v83
	v_cndmask_b32_e32 v67, v67, v82, vcc
	v_rsq_f32_e32 v67, v67
	v_mul_f32_e32 v80, v80, v83
	v_mul_f32_e32 v83, 0xbfb8aa3b, v76
	v_mul_f32_e32 v82, 0x45800000, v67
	v_cndmask_b32_e32 v82, v67, v82, vcc
	v_exp_f32_e32 v83, v83
	s_waitcnt vmcnt(9)
	v_lshlrev_b32_e32 v67, 16, v186
	v_sub_f32_e32 v67, v67, v66
	v_mul_f32_e32 v67, v67, v82
	v_mul_f32_e32 v67, v151, v67
	v_mul_f32_e32 v67, v80, v67
	v_add_f32_e32 v83, 1.0, v83
	v_rcp_f32_e32 v83, v83
	v_cvt_pk_bf16_f32 v67, v67, s0
	v_mul_f32_e32 v76, v76, v83
	v_mul_f32_e32 v83, 0xbfb8aa3b, v72
	v_exp_f32_e32 v83, v83
	s_waitcnt vmcnt(8)
	v_lshlrev_b32_e32 v80, 16, v187
	v_sub_f32_e32 v80, v80, v66
	v_mul_f32_e32 v80, v80, v82
	v_mul_f32_e32 v80, v150, v80
	v_mul_f32_e32 v76, v76, v80
	v_add_f32_e32 v83, 1.0, v83
	v_rcp_f32_e32 v83, v83
	v_cvt_pk_bf16_f32 v76, v76, s0
	v_mul_f32_e32 v72, v72, v83
	s_waitcnt vmcnt(7)
	v_lshlrev_b32_e32 v80, 16, v188
	v_sub_f32_e32 v80, v80, v66
	v_mul_f32_e32 v80, v80, v82
	v_mul_f32_e32 v80, v149, v80
	v_mul_f32_e32 v72, v72, v80
	v_cvt_pk_bf16_f32 v72, v72, s0
	s_waitcnt vmcnt(6)
	v_lshlrev_b32_e32 v80, 16, v189
	v_sub_f32_e32 v66, v80, v66
	v_mul_f32_e32 v80, 0xbfb8aa3b, v68
	v_exp_f32_e32 v80, v80
	v_mul_f32_e32 v66, v66, v82
	v_mul_f32_e32 v66, v148, v66
	v_add_f32_e32 v80, 1.0, v80
	v_rcp_f32_e32 v80, v80
	s_nop 0
	v_mul_f32_e32 v68, v68, v80
	v_mul_f32_e32 v66, v68, v66
	s_nop 0
	s_nop 0
	v_cvt_pk_bf16_f32 v66, v66, s0
	global_store_short v[92:93], v0, off
	global_store_short v[92:93], v74, off offset:32
	global_store_short v[92:93], v70, off offset:256
	global_store_short v[92:93], v78, off offset:288
	global_store_short v[94:95], v79, off
	global_store_short v[94:95], v75, off offset:32
	global_store_short v[94:95], v71, off offset:256
	global_store_short v[94:95], v98, off offset:288
	global_store_short v[96:97], v67, off
	global_store_short v[96:97], v76, off offset:32
	global_store_short v[96:97], v72, off offset:256
	global_store_short v[96:97], v66, off offset:288
	v_add_u32_e32 v70, 0x80, v152
	s_waitcnt vmcnt(16)
	v_pk_add_f32 v[66:67], v[214:215], v[216:217]
	s_nop 0
	v_pk_add_f32 v[66:67], v[66:67], v[210:211]
	s_nop 0
	v_pk_add_f32 v[66:67], v[66:67], v[212:213]
	s_nop 0
	v_pk_mul_f32 v[66:67], v[66:67], s[18:19] op_sel_hi:[1,0]
	s_nop 0
	v_fma_f32 v0, -v66, v66, v67
	v_max_f32_e32 v0, 0, v0
	v_add_f32_e32 v0, 0x3727c5ac, v0
	v_cmp_gt_f32_e32 vcc, s25, v0
	v_mul_f32_e32 v67, 0x4b800000, v0
	s_nop 0
	v_cndmask_b32_e32 v0, v0, v67, vcc
	v_rsq_f32_e32 v0, v0
	s_nop 0
	v_mul_f32_e32 v67, 0x45800000, v0
	v_cndmask_b32_e32 v0, v0, v67, vcc
	s_waitcnt vmcnt(15)
	v_lshlrev_b32_e32 v67, 16, v190
	v_mul_f32_e32 v68, 0xbfb8aa3b, v81
	v_exp_f32_e32 v68, v68
	v_sub_f32_e32 v67, v67, v66
	v_mul_f32_e32 v67, v67, v0
	v_mul_f32_e32 v67, v151, v67
	v_add_f32_e32 v68, 1.0, v68
	v_rcp_f32_e32 v68, v68
	s_nop 0
	v_mul_f32_e32 v68, v81, v68
	v_mul_f32_e32 v67, v68, v67
	v_mul_f32_e32 v68, 0xbfb8aa3b, v77
	v_exp_f32_e32 v68, v68
	v_cvt_pk_bf16_f32 v67, v67, s0
	global_store_short v[90:91], v67, off
	s_waitcnt vmcnt(15)
	v_lshlrev_b32_e32 v67, 16, v191
	v_add_f32_e32 v68, 1.0, v68
	v_rcp_f32_e32 v68, v68
	v_sub_f32_e32 v67, v67, v66
	v_mul_f32_e32 v67, v67, v0
	v_mul_f32_e32 v67, v150, v67
	v_mul_f32_e32 v68, v77, v68
	v_mul_f32_e32 v67, v68, v67
	v_mul_f32_e32 v68, 0xbfb8aa3b, v73
	v_exp_f32_e32 v68, v68
	v_cvt_pk_bf16_f32 v67, v67, s0
	global_store_short v[90:91], v67, off offset:32
	s_waitcnt vmcnt(15)
	v_lshlrev_b32_e32 v67, 16, v192
	v_add_f32_e32 v68, 1.0, v68
	v_rcp_f32_e32 v68, v68
	v_sub_f32_e32 v67, v67, v66
	v_mul_f32_e32 v67, v67, v0
	v_mul_f32_e32 v67, v149, v67
	v_mul_f32_e32 v68, v73, v68
	v_mul_f32_e32 v67, v68, v67
	v_cvt_pk_bf16_f32 v67, v67, s0
	global_store_short v[90:91], v67, off offset:256
	s_waitcnt vmcnt(15)
; __device__ __forceinline__ float bf2f(u16 b) { return __uint_as_float(((unsigned)b) << 16); }
; __device__ __forceinline__ float silu_f(float g) { return g * __builtin_amdgcn_rcpf(1.f + __builtin_amdgcn_exp2f(-g * LOG2E)); }
; template <int EPI>
; __device__ __forceinline__ void epilogue(const Params& p, int pass, int layer, int pm, int pn,
;                                          f32x4 (&acc)[2][2][4][2], const float* xin, float* xout) {
;     ...
;         int tb = t0 + ai * 128 + wr * 64 + m * 16 + fq * 4;
;         asm volatile("" : "+v"(tb));
;         float4 s01[4], s23[4];
;         u16 yv[4][2][2];
; #pragma unroll
;         for (int j = 0; j < 4; ++j) {
;           const float4* sp = (const float4*)(stat + ((long)(tb + j) * 8 + h) * 8);
;           s01[j] = sp[0]; s23[j] = sp[1];
; #pragma unroll
;           for (int bj = 0; bj < 2; ++bj)
; #pragma unroll
;             for (int n = 0; n < 2; ++n)
;               yv[j][bj][n] = Y[(long)(tb + j) * YS + pn * 256 + bj * 128 + wc * 32 + n * 16 + fr];
;         }
; #pragma unroll
;         for (int j = 0; j < 4; ++j) {
;           float s1 = s01[j].x + s01[j].z + s23[j].x + s23[j].z, s2 = s01[j].y + s01[j].w + s23[j].y + s23[j].w;
;           float mu = s1 * (1.f / 512.f);
;           float var = s2 * (1.f / 512.f) - mu * mu;
;           float rstd = rsqrtf(fmaxf(var, 0.f) + 1e-5f);
; #pragma unroll
;           for (int bj = 0; bj < 2; ++bj)
; #pragma unroll
;             for (int n = 0; n < 2; ++n) {
;               float g = acc[ai][bj][m][n][j];
;               float yn = (bf2f(yv[j][bj][n]) - mu) * rstd * gn[bj][n];
;               Y[(long)(tb + j) * YS + pn * 256 + bj * 128 + wc * 32 + n * 16 + fr] = f2bf(silu_f(g) * yn);
;             }
	v_lshlrev_b32_e32 v67, 16, v193
	v_sub_f32_e32 v66, v67, v66
	v_mul_f32_e32 v0, v66, v0
	v_mul_f32_e32 v66, 0xbfb8aa3b, v69
	v_exp_f32_e32 v66, v66
	v_mul_f32_e32 v0, v148, v0
	v_add_f32_e32 v66, 1.0, v66
	v_rcp_f32_e32 v66, v66
	s_nop 0
	v_mul_f32_e32 v66, v69, v66
	v_mul_f32_e32 v0, v66, v0
	v_cvt_pk_bf16_f32 v0, v0, s0
	global_store_short v[90:91], v0, off offset:288
	s_nop 0
	v_ashrrev_i32_e32 v71, 31, v70
	v_lshlrev_b64 v[66:67], 8, v[70:71]
	v_lshl_add_u64 v[72:73], s[16:17], 0, v[66:67]
	global_load_dwordx4 v[82:85], v[72:73], off offset:16
	global_load_dwordx4 v[86:89], v[72:73], off
	v_mad_i64_i32 v[76:77], s[14:15], v70, s24, v[138:139]
	global_load_ushort v162, v[76:77], off
	global_load_ushort v163, v[76:77], off offset:32
	global_load_ushort v164, v[76:77], off offset:256
	global_load_ushort v165, v[76:77], off offset:288
	v_add_u32_e32 v66, 1, v70
	v_ashrrev_i32_e32 v67, 31, v66
	v_lshlrev_b64 v[68:69], 8, v[66:67]
	v_lshl_add_u64 v[68:69], s[16:17], 0, v[68:69]
	global_load_dwordx4 v[194:197], v[68:69], off offset:16
	global_load_dwordx4 v[198:201], v[68:69], off
	v_mad_i64_i32 v[78:79], s[14:15], v66, s24, v[138:139]
	global_load_ushort v166, v[78:79], off
	global_load_ushort v167, v[78:79], off offset:32
	global_load_ushort v168, v[78:79], off offset:256
	global_load_ushort v169, v[78:79], off offset:288
	v_add_u32_e32 v74, 2, v70
	v_ashrrev_i32_e32 v75, 31, v74
	v_lshlrev_b64 v[66:67], 8, v[74:75]
	v_lshl_add_u64 v[66:67], s[16:17], 0, v[66:67]
	global_load_dwordx4 v[202:205], v[66:67], off offset:16
	global_load_dwordx4 v[206:209], v[66:67], off
	v_mad_i64_i32 v[80:81], s[14:15], v74, s24, v[138:139]
	global_load_ushort v170, v[80:81], off
	global_load_ushort v171, v[80:81], off offset:32
	global_load_ushort v172, v[80:81], off offset:256
	global_load_ushort v173, v[80:81], off offset:288
	v_add_u32_e32 v74, 3, v70
	v_ashrrev_i32_e32 v75, 31, v74
	v_lshlrev_b64 v[70:71], 8, v[74:75]
	v_lshl_add_u64 v[70:71], s[16:17], 0, v[70:71]
	global_load_dwordx4 v[210:213], v[70:71], off offset:16
	global_load_dwordx4 v[214:217], v[70:71], off
	v_mad_i64_i32 v[74:75], s[14:15], v74, s24, v[138:139]
	global_load_ushort v174, v[74:75], off
	global_load_ushort v175, v[74:75], off offset:32
	global_load_ushort v176, v[74:75], off offset:256
	global_load_ushort v177, v[74:75], off offset:288
	s_waitcnt vmcnt(22)
	v_pk_add_f32 v[72:73], v[86:87], v[88:89]
	s_nop 0
	v_pk_add_f32 v[72:73], v[72:73], v[82:83]
	v_mul_f32_e32 v82, 0xbfb8aa3b, v62
	v_pk_add_f32 v[72:73], v[72:73], v[84:85]
	v_exp_f32_e32 v82, v82
	v_pk_mul_f32 v[72:73], v[72:73], s[18:19] op_sel_hi:[1,0]
	v_add_f32_e32 v82, 1.0, v82
	v_fma_f32 v0, -v72, v72, v73
	v_max_f32_e32 v0, 0, v0
	v_add_f32_e32 v0, 0x3727c5ac, v0
	v_cmp_gt_f32_e32 vcc, s25, v0
	v_mul_f32_e32 v73, 0x4b800000, v0
	v_rcp_f32_e32 v82, v82
	v_cndmask_b32_e32 v0, v0, v73, vcc
	v_rsq_f32_e32 v0, v0
	v_mul_f32_e32 v62, v62, v82
	v_mul_f32_e32 v82, 0xbfb8aa3b, v58
	v_mul_f32_e32 v73, 0x45800000, v0
	v_cndmask_b32_e32 v73, v0, v73, vcc
	v_exp_f32_e32 v82, v82
	s_waitcnt vmcnt(21)
	v_lshlrev_b32_e32 v0, 16, v162
	v_sub_f32_e32 v0, v0, v72
	v_mul_f32_e32 v0, v0, v73
	v_mul_f32_e32 v0, v151, v0
	v_mul_f32_e32 v0, v62, v0
	v_add_f32_e32 v82, 1.0, v82
	v_rcp_f32_e32 v82, v82
	v_cvt_pk_bf16_f32 v0, v0, s0
	v_mul_f32_e32 v58, v58, v82
	v_mul_f32_e32 v82, 0xbfb8aa3b, v54
	v_exp_f32_e32 v82, v82
	s_waitcnt vmcnt(20)
	v_lshlrev_b32_e32 v62, 16, v163
	v_sub_f32_e32 v62, v62, v72
	v_mul_f32_e32 v62, v62, v73
	v_mul_f32_e32 v62, v150, v62
	v_mul_f32_e32 v58, v58, v62
	v_add_f32_e32 v82, 1.0, v82
	v_rcp_f32_e32 v82, v82
	v_cvt_pk_bf16_f32 v58, v58, s0
	v_mul_f32_e32 v54, v54, v82
	s_waitcnt vmcnt(19)
	v_lshlrev_b32_e32 v62, 16, v164
	v_sub_f32_e32 v62, v62, v72
	v_mul_f32_e32 v62, v62, v73
	v_mul_f32_e32 v62, v149, v62
	v_mul_f32_e32 v54, v54, v62
	v_cvt_pk_bf16_f32 v54, v54, s0
	s_waitcnt vmcnt(18)
	v_lshlrev_b32_e32 v62, 16, v165
	v_sub_f32_e32 v62, v62, v72
	v_mul_f32_e32 v72, 0xbfb8aa3b, v50
	v_exp_f32_e32 v72, v72
	s_waitcnt vmcnt(16)
	v_pk_add_f32 v[68:69], v[198:199], v[200:201]
	v_mul_f32_e32 v62, v62, v73
	v_pk_add_f32 v[68:69], v[68:69], v[194:195]
	v_add_f32_e32 v72, 1.0, v72
	v_rcp_f32_e32 v72, v72
	v_mul_f32_e32 v62, v148, v62
	v_pk_add_f32 v[68:69], v[68:69], v[196:197]
	v_mul_f32_e32 v50, v50, v72
	v_mul_f32_e32 v50, v50, v62
	v_pk_mul_f32 v[68:69], v[68:69], s[18:19] op_sel_hi:[1,0]
	v_cvt_pk_bf16_f32 v62, v50, s0
	v_fma_f32 v50, -v68, v68, v69
	v_max_f32_e32 v50, 0, v50
	v_add_f32_e32 v50, 0x3727c5ac, v50
	v_cmp_gt_f32_e32 vcc, s25, v50
	v_mul_f32_e32 v69, 0x4b800000, v50
	v_mul_f32_e32 v72, 0xbfb8aa3b, v63
	v_cndmask_b32_e32 v50, v50, v69, vcc
	v_rsq_f32_e32 v50, v50
	v_exp_f32_e32 v72, v72
	v_mul_f32_e32 v69, 0x45800000, v50
	v_cndmask_b32_e32 v50, v50, v69, vcc
	v_add_f32_e32 v72, 1.0, v72
	v_rcp_f32_e32 v72, v72
	s_waitcnt vmcnt(15)
	v_lshlrev_b32_e32 v69, 16, v166
	v_sub_f32_e32 v69, v69, v68
	v_mul_f32_e32 v69, v69, v50
	v_mul_f32_e32 v69, v151, v69
	v_mul_f32_e32 v63, v63, v72
	v_mul_f32_e32 v63, v63, v69
	v_mul_f32_e32 v72, 0xbfb8aa3b, v59
	v_exp_f32_e32 v72, v72
	v_cvt_pk_bf16_f32 v63, v63, s0
	v_add_f32_e32 v72, 1.0, v72
	v_rcp_f32_e32 v72, v72
	s_waitcnt vmcnt(14)
	v_lshlrev_b32_e32 v69, 16, v167
	v_sub_f32_e32 v69, v69, v68
	v_mul_f32_e32 v69, v69, v50
	v_mul_f32_e32 v69, v150, v69
	v_mul_f32_e32 v59, v59, v72
	v_mul_f32_e32 v59, v59, v69
	v_mul_f32_e32 v72, 0xbfb8aa3b, v55
	v_exp_f32_e32 v72, v72
	v_cvt_pk_bf16_f32 v59, v59, s0
	v_add_f32_e32 v72, 1.0, v72
	v_rcp_f32_e32 v72, v72
	s_waitcnt vmcnt(13)
; __device__ __forceinline__ float bf2f(u16 b) { return __uint_as_float(((unsigned)b) << 16); }
; __device__ __forceinline__ float silu_f(float g) { return g * __builtin_amdgcn_rcpf(1.f + __builtin_amdgcn_exp2f(-g * LOG2E)); }
; template <int EPI>
; __device__ __forceinline__ void epilogue(const Params& p, int pass, int layer, int pm, int pn,
;                                          f32x4 (&acc)[2][2][4][2], const float* xin, float* xout) {
;     ...
;         for (int j = 0; j < 4; ++j) {
;           float s1 = s01[j].x + s01[j].z + s23[j].x + s23[j].z, s2 = s01[j].y + s01[j].w + s23[j].y + s23[j].w;
;           float mu = s1 * (1.f / 512.f);
;           float var = s2 * (1.f / 512.f) - mu * mu;
;           float rstd = rsqrtf(fmaxf(var, 0.f) + 1e-5f);
; #pragma unroll
;           for (int bj = 0; bj < 2; ++bj)
; #pragma unroll
;             for (int n = 0; n < 2; ++n) {
;               float g = acc[ai][bj][m][n][j];
;               float yn = (bf2f(yv[j][bj][n]) - mu) * rstd * gn[bj][n];
;               Y[(long)(tb + j) * YS + pn * 256 + bj * 128 + wc * 32 + n * 16 + fr] = f2bf(silu_f(g) * yn);
;             }
	v_lshlrev_b32_e32 v69, 16, v168
	v_sub_f32_e32 v69, v69, v68
	v_mul_f32_e32 v69, v69, v50
	v_mul_f32_e32 v69, v149, v69
	v_mul_f32_e32 v55, v55, v72
	v_mul_f32_e32 v55, v55, v69
	v_cvt_pk_bf16_f32 v55, v55, s0
	s_waitcnt vmcnt(12)
	v_lshlrev_b32_e32 v69, 16, v169
	v_sub_f32_e32 v68, v69, v68
	v_mul_f32_e32 v50, v68, v50
	v_mul_f32_e32 v68, 0xbfb8aa3b, v51
	v_exp_f32_e32 v68, v68
	v_mul_f32_e32 v50, v148, v50
	v_add_f32_e32 v68, 1.0, v68
	v_rcp_f32_e32 v68, v68
	s_nop 0
	v_mul_f32_e32 v51, v51, v68
	s_nop 0
	v_mul_f32_e32 v50, v51, v50
	v_cvt_pk_bf16_f32 v82, v50, s0
	s_waitcnt vmcnt(10)
	v_pk_add_f32 v[50:51], v[206:207], v[208:209]
	s_nop 0
	v_pk_add_f32 v[50:51], v[50:51], v[202:203]
	v_mul_f32_e32 v67, 0xbfb8aa3b, v64
	v_pk_add_f32 v[50:51], v[50:51], v[204:205]
	v_exp_f32_e32 v67, v67
	v_pk_mul_f32 v[50:51], v[50:51], s[18:19] op_sel_hi:[1,0]
	v_add_f32_e32 v67, 1.0, v67
	v_fma_f32 v51, -v50, v50, v51
	v_max_f32_e32 v51, 0, v51
	v_add_f32_e32 v51, 0x3727c5ac, v51
	v_cmp_gt_f32_e32 vcc, s25, v51
	v_mul_f32_e32 v66, 0x4b800000, v51
	v_rcp_f32_e32 v67, v67
	v_cndmask_b32_e32 v51, v51, v66, vcc
	v_rsq_f32_e32 v51, v51
	v_mul_f32_e32 v64, v64, v67
	v_mul_f32_e32 v67, 0xbfb8aa3b, v60
	v_mul_f32_e32 v66, 0x45800000, v51
	v_cndmask_b32_e32 v66, v51, v66, vcc
	v_exp_f32_e32 v67, v67
	s_waitcnt vmcnt(9)
	v_lshlrev_b32_e32 v51, 16, v170
	v_sub_f32_e32 v51, v51, v50
	v_mul_f32_e32 v51, v51, v66
	v_mul_f32_e32 v51, v151, v51
	v_mul_f32_e32 v51, v64, v51
	v_add_f32_e32 v67, 1.0, v67
	v_rcp_f32_e32 v67, v67
	v_cvt_pk_bf16_f32 v51, v51, s0
	v_mul_f32_e32 v60, v60, v67
	v_mul_f32_e32 v67, 0xbfb8aa3b, v56
	v_exp_f32_e32 v67, v67
	s_waitcnt vmcnt(8)
	v_lshlrev_b32_e32 v64, 16, v171
	v_sub_f32_e32 v64, v64, v50
	v_mul_f32_e32 v64, v64, v66
	v_mul_f32_e32 v64, v150, v64
	v_mul_f32_e32 v60, v60, v64
	v_add_f32_e32 v67, 1.0, v67
	v_rcp_f32_e32 v67, v67
	v_cvt_pk_bf16_f32 v60, v60, s0
	v_mul_f32_e32 v56, v56, v67
	s_waitcnt vmcnt(7)
	v_lshlrev_b32_e32 v64, 16, v172
	v_sub_f32_e32 v64, v64, v50
	v_mul_f32_e32 v64, v64, v66
	v_mul_f32_e32 v64, v149, v64
	v_mul_f32_e32 v56, v56, v64
	v_cvt_pk_bf16_f32 v56, v56, s0
	s_waitcnt vmcnt(6)
	v_lshlrev_b32_e32 v64, 16, v173
	v_sub_f32_e32 v50, v64, v50
	v_mul_f32_e32 v64, 0xbfb8aa3b, v52
	v_exp_f32_e32 v64, v64
	v_mul_f32_e32 v50, v50, v66
	v_mul_f32_e32 v50, v148, v50
	v_add_f32_e32 v64, 1.0, v64
	v_rcp_f32_e32 v64, v64
	s_nop 0
	v_mul_f32_e32 v52, v52, v64
	v_mul_f32_e32 v50, v52, v50
	s_nop 0
	s_nop 0
	v_cvt_pk_bf16_f32 v50, v50, s0
	global_store_short v[76:77], v0, off
	global_store_short v[76:77], v58, off offset:32
	global_store_short v[76:77], v54, off offset:256
	global_store_short v[76:77], v62, off offset:288
	global_store_short v[78:79], v63, off
	global_store_short v[78:79], v59, off offset:32
	global_store_short v[78:79], v55, off offset:256
	global_store_short v[78:79], v82, off offset:288
	global_store_short v[80:81], v51, off
	global_store_short v[80:81], v60, off offset:32
	global_store_short v[80:81], v56, off offset:256
	global_store_short v[80:81], v50, off offset:288
	v_add_u32_e32 v54, 0x90, v152
	s_waitcnt vmcnt(16)
	v_pk_add_f32 v[50:51], v[214:215], v[216:217]
	s_nop 0
	v_pk_add_f32 v[50:51], v[50:51], v[210:211]
	s_nop 0
	v_pk_add_f32 v[50:51], v[50:51], v[212:213]
	s_nop 0
	v_pk_mul_f32 v[50:51], v[50:51], s[18:19] op_sel_hi:[1,0]
	s_nop 0
	v_fma_f32 v0, -v50, v50, v51
	v_max_f32_e32 v0, 0, v0
	v_add_f32_e32 v0, 0x3727c5ac, v0
	v_cmp_gt_f32_e32 vcc, s25, v0
	v_mul_f32_e32 v51, 0x4b800000, v0
	s_nop 0
	v_cndmask_b32_e32 v0, v0, v51, vcc
	v_rsq_f32_e32 v0, v0
	s_nop 0
	v_mul_f32_e32 v51, 0x45800000, v0
	v_cndmask_b32_e32 v0, v0, v51, vcc
	s_waitcnt vmcnt(15)
	v_lshlrev_b32_e32 v51, 16, v174
	v_mul_f32_e32 v52, 0xbfb8aa3b, v65
	v_exp_f32_e32 v52, v52
	v_sub_f32_e32 v51, v51, v50
	v_mul_f32_e32 v51, v51, v0
	v_mul_f32_e32 v51, v151, v51
	v_add_f32_e32 v52, 1.0, v52
	v_rcp_f32_e32 v52, v52
	s_nop 0
	v_mul_f32_e32 v52, v65, v52
	v_mul_f32_e32 v51, v52, v51
	v_mul_f32_e32 v52, 0xbfb8aa3b, v61
	v_exp_f32_e32 v52, v52
	v_cvt_pk_bf16_f32 v51, v51, s0
	global_store_short v[74:75], v51, off
	s_waitcnt vmcnt(15)
	v_lshlrev_b32_e32 v51, 16, v175
	v_add_f32_e32 v52, 1.0, v52
	v_rcp_f32_e32 v52, v52
	v_sub_f32_e32 v51, v51, v50
	v_mul_f32_e32 v51, v51, v0
	v_mul_f32_e32 v51, v150, v51
	v_mul_f32_e32 v52, v61, v52
	v_mul_f32_e32 v51, v52, v51
	v_mul_f32_e32 v52, 0xbfb8aa3b, v57
	v_exp_f32_e32 v52, v52
	v_cvt_pk_bf16_f32 v51, v51, s0
	global_store_short v[74:75], v51, off offset:32
	s_waitcnt vmcnt(15)
	v_lshlrev_b32_e32 v51, 16, v176
	v_add_f32_e32 v52, 1.0, v52
	v_rcp_f32_e32 v52, v52
	v_sub_f32_e32 v51, v51, v50
	v_mul_f32_e32 v51, v51, v0
	v_mul_f32_e32 v51, v149, v51
	v_mul_f32_e32 v52, v57, v52
	v_mul_f32_e32 v51, v52, v51
	v_cvt_pk_bf16_f32 v51, v51, s0
	global_store_short v[74:75], v51, off offset:256
	s_waitcnt vmcnt(15)
; __device__ __forceinline__ float bf2f(u16 b) { return __uint_as_float(((unsigned)b) << 16); }
; __device__ __forceinline__ float silu_f(float g) { return g * __builtin_amdgcn_rcpf(1.f + __builtin_amdgcn_exp2f(-g * LOG2E)); }
; template <int EPI>
; __device__ __forceinline__ void epilogue(const Params& p, int pass, int layer, int pm, int pn,
;                                          f32x4 (&acc)[2][2][4][2], const float* xin, float* xout) {
;     ...
;         int tb = t0 + ai * 128 + wr * 64 + m * 16 + fq * 4;
;         asm volatile("" : "+v"(tb));
;         float4 s01[4], s23[4];
;         u16 yv[4][2][2];
; #pragma unroll
;         for (int j = 0; j < 4; ++j) {
;           const float4* sp = (const float4*)(stat + ((long)(tb + j) * 8 + h) * 8);
;           s01[j] = sp[0]; s23[j] = sp[1];
; #pragma unroll
;           for (int bj = 0; bj < 2; ++bj)
; #pragma unroll
;             for (int n = 0; n < 2; ++n)
;               yv[j][bj][n] = Y[(long)(tb + j) * YS + pn * 256 + bj * 128 + wc * 32 + n * 16 + fr];
;         }
; #pragma unroll
;         for (int j = 0; j < 4; ++j) {
;           float s1 = s01[j].x + s01[j].z + s23[j].x + s23[j].z, s2 = s01[j].y + s01[j].w + s23[j].y + s23[j].w;
;           float mu = s1 * (1.f / 512.f);
;           float var = s2 * (1.f / 512.f) - mu * mu;
;           float rstd = rsqrtf(fmaxf(var, 0.f) + 1e-5f);
; #pragma unroll
;           for (int bj = 0; bj < 2; ++bj)
; #pragma unroll
;             for (int n = 0; n < 2; ++n) {
;               float g = acc[ai][bj][m][n][j];
;               float yn = (bf2f(yv[j][bj][n]) - mu) * rstd * gn[bj][n];
;               Y[(long)(tb + j) * YS + pn * 256 + bj * 128 + wc * 32 + n * 16 + fr] = f2bf(silu_f(g) * yn);
;             }
	v_lshlrev_b32_e32 v51, 16, v177
	v_sub_f32_e32 v50, v51, v50
	v_mul_f32_e32 v0, v50, v0
	v_mul_f32_e32 v50, 0xbfb8aa3b, v53
	v_exp_f32_e32 v50, v50
	v_mul_f32_e32 v0, v148, v0
	v_add_f32_e32 v50, 1.0, v50
	v_rcp_f32_e32 v50, v50
	s_nop 0
	v_mul_f32_e32 v50, v53, v50
	v_mul_f32_e32 v0, v50, v0
	v_cvt_pk_bf16_f32 v0, v0, s0
	global_store_short v[74:75], v0, off offset:288
	s_nop 0
	v_ashrrev_i32_e32 v55, 31, v54
	v_lshlrev_b64 v[50:51], 8, v[54:55]
	v_lshl_add_u64 v[56:57], s[16:17], 0, v[50:51]
	global_load_dwordx4 v[66:69], v[56:57], off offset:16
	global_load_dwordx4 v[70:73], v[56:57], off
	v_mad_i64_i32 v[60:61], s[14:15], v54, s24, v[138:139]
	global_load_ushort v178, v[60:61], off
	global_load_ushort v179, v[60:61], off offset:32
	global_load_ushort v180, v[60:61], off offset:256
	global_load_ushort v181, v[60:61], off offset:288
	v_add_u32_e32 v50, 1, v54
	v_ashrrev_i32_e32 v51, 31, v50
	v_lshlrev_b64 v[52:53], 8, v[50:51]
	v_lshl_add_u64 v[52:53], s[16:17], 0, v[52:53]
	global_load_dwordx4 v[194:197], v[52:53], off offset:16
	global_load_dwordx4 v[198:201], v[52:53], off
	v_mad_i64_i32 v[62:63], s[14:15], v50, s24, v[138:139]
	global_load_ushort v182, v[62:63], off
	global_load_ushort v183, v[62:63], off offset:32
	global_load_ushort v184, v[62:63], off offset:256
	global_load_ushort v185, v[62:63], off offset:288
	v_add_u32_e32 v58, 2, v54
	v_ashrrev_i32_e32 v59, 31, v58
	v_lshlrev_b64 v[50:51], 8, v[58:59]
	v_lshl_add_u64 v[50:51], s[16:17], 0, v[50:51]
	global_load_dwordx4 v[202:205], v[50:51], off offset:16
	global_load_dwordx4 v[206:209], v[50:51], off
	v_mad_i64_i32 v[64:65], s[14:15], v58, s24, v[138:139]
	global_load_ushort v186, v[64:65], off
	global_load_ushort v187, v[64:65], off offset:32
	global_load_ushort v188, v[64:65], off offset:256
	global_load_ushort v189, v[64:65], off offset:288
	v_add_u32_e32 v58, 3, v54
	v_ashrrev_i32_e32 v59, 31, v58
	v_lshlrev_b64 v[54:55], 8, v[58:59]
	v_lshl_add_u64 v[54:55], s[16:17], 0, v[54:55]
	global_load_dwordx4 v[210:213], v[54:55], off offset:16
	global_load_dwordx4 v[214:217], v[54:55], off
	v_mad_i64_i32 v[58:59], s[14:15], v58, s24, v[138:139]
	global_load_ushort v190, v[58:59], off
	global_load_ushort v191, v[58:59], off offset:32
	global_load_ushort v192, v[58:59], off offset:256
	global_load_ushort v193, v[58:59], off offset:288
	s_waitcnt vmcnt(22)
	v_pk_add_f32 v[56:57], v[70:71], v[72:73]
	s_nop 0
	v_pk_add_f32 v[56:57], v[56:57], v[66:67]
	v_mul_f32_e32 v66, 0xbfb8aa3b, v46
	v_pk_add_f32 v[56:57], v[56:57], v[68:69]
	v_exp_f32_e32 v66, v66
	v_pk_mul_f32 v[56:57], v[56:57], s[18:19] op_sel_hi:[1,0]
	v_add_f32_e32 v66, 1.0, v66
	v_fma_f32 v0, -v56, v56, v57
	v_max_f32_e32 v0, 0, v0
	v_add_f32_e32 v0, 0x3727c5ac, v0
	v_cmp_gt_f32_e32 vcc, s25, v0
	v_mul_f32_e32 v57, 0x4b800000, v0
	v_rcp_f32_e32 v66, v66
	v_cndmask_b32_e32 v0, v0, v57, vcc
	v_rsq_f32_e32 v0, v0
	v_mul_f32_e32 v46, v46, v66
	v_mul_f32_e32 v66, 0xbfb8aa3b, v42
	v_mul_f32_e32 v57, 0x45800000, v0
	v_cndmask_b32_e32 v57, v0, v57, vcc
	v_exp_f32_e32 v66, v66
	s_waitcnt vmcnt(21)
	v_lshlrev_b32_e32 v0, 16, v178
	v_sub_f32_e32 v0, v0, v56
	v_mul_f32_e32 v0, v0, v57
	v_mul_f32_e32 v0, v151, v0
	v_mul_f32_e32 v0, v46, v0
	v_add_f32_e32 v66, 1.0, v66
	v_rcp_f32_e32 v66, v66
	v_cvt_pk_bf16_f32 v0, v0, s0
	v_mul_f32_e32 v42, v42, v66
	v_mul_f32_e32 v66, 0xbfb8aa3b, v38
	v_exp_f32_e32 v66, v66
	s_waitcnt vmcnt(20)
	v_lshlrev_b32_e32 v46, 16, v179
	v_sub_f32_e32 v46, v46, v56
	v_mul_f32_e32 v46, v46, v57
	v_mul_f32_e32 v46, v150, v46
	v_mul_f32_e32 v42, v42, v46
	v_add_f32_e32 v66, 1.0, v66
	v_rcp_f32_e32 v66, v66
	v_cvt_pk_bf16_f32 v42, v42, s0
	v_mul_f32_e32 v38, v38, v66
	s_waitcnt vmcnt(19)
	v_lshlrev_b32_e32 v46, 16, v180
	v_sub_f32_e32 v46, v46, v56
	v_mul_f32_e32 v46, v46, v57
	v_mul_f32_e32 v46, v149, v46
	v_mul_f32_e32 v38, v38, v46
	v_cvt_pk_bf16_f32 v38, v38, s0
	s_waitcnt vmcnt(18)
	v_lshlrev_b32_e32 v46, 16, v181
	v_sub_f32_e32 v46, v46, v56
	v_mul_f32_e32 v56, 0xbfb8aa3b, v34
	v_exp_f32_e32 v56, v56
	s_waitcnt vmcnt(16)
	v_pk_add_f32 v[52:53], v[198:199], v[200:201]
	v_mul_f32_e32 v46, v46, v57
	v_pk_add_f32 v[52:53], v[52:53], v[194:195]
	v_add_f32_e32 v56, 1.0, v56
	v_rcp_f32_e32 v56, v56
	v_mul_f32_e32 v46, v148, v46
	v_pk_add_f32 v[52:53], v[52:53], v[196:197]
	v_mul_f32_e32 v34, v34, v56
	v_mul_f32_e32 v34, v34, v46
	v_pk_mul_f32 v[52:53], v[52:53], s[18:19] op_sel_hi:[1,0]
	v_cvt_pk_bf16_f32 v46, v34, s0
	v_fma_f32 v34, -v52, v52, v53
	v_max_f32_e32 v34, 0, v34
	v_add_f32_e32 v34, 0x3727c5ac, v34
	v_cmp_gt_f32_e32 vcc, s25, v34
	v_mul_f32_e32 v53, 0x4b800000, v34
	v_mul_f32_e32 v56, 0xbfb8aa3b, v47
	v_cndmask_b32_e32 v34, v34, v53, vcc
	v_rsq_f32_e32 v34, v34
	v_exp_f32_e32 v56, v56
	v_mul_f32_e32 v53, 0x45800000, v34
	v_cndmask_b32_e32 v34, v34, v53, vcc
	v_add_f32_e32 v56, 1.0, v56
	v_rcp_f32_e32 v56, v56
	s_waitcnt vmcnt(15)
	v_lshlrev_b32_e32 v53, 16, v182
	v_sub_f32_e32 v53, v53, v52
	v_mul_f32_e32 v53, v53, v34
	v_mul_f32_e32 v53, v151, v53
	v_mul_f32_e32 v47, v47, v56
	v_mul_f32_e32 v47, v47, v53
	v_mul_f32_e32 v56, 0xbfb8aa3b, v43
	v_exp_f32_e32 v56, v56
	v_cvt_pk_bf16_f32 v47, v47, s0
	v_add_f32_e32 v56, 1.0, v56
	v_rcp_f32_e32 v56, v56
	s_waitcnt vmcnt(14)
	v_lshlrev_b32_e32 v53, 16, v183
	v_sub_f32_e32 v53, v53, v52
	v_mul_f32_e32 v53, v53, v34
	v_mul_f32_e32 v53, v150, v53
	v_mul_f32_e32 v43, v43, v56
	v_mul_f32_e32 v43, v43, v53
	v_mul_f32_e32 v56, 0xbfb8aa3b, v39
	v_exp_f32_e32 v56, v56
	v_cvt_pk_bf16_f32 v43, v43, s0
	v_add_f32_e32 v56, 1.0, v56
	v_rcp_f32_e32 v56, v56
	s_waitcnt vmcnt(13)
; __device__ __forceinline__ float bf2f(u16 b) { return __uint_as_float(((unsigned)b) << 16); }
; __device__ __forceinline__ float silu_f(float g) { return g * __builtin_amdgcn_rcpf(1.f + __builtin_amdgcn_exp2f(-g * LOG2E)); }
; template <int EPI>
; __device__ __forceinline__ void epilogue(const Params& p, int pass, int layer, int pm, int pn,
;                                          f32x4 (&acc)[2][2][4][2], const float* xin, float* xout) {
;     ...
;         for (int j = 0; j < 4; ++j) {
;           float s1 = s01[j].x + s01[j].z + s23[j].x + s23[j].z, s2 = s01[j].y + s01[j].w + s23[j].y + s23[j].w;
;           float mu = s1 * (1.f / 512.f);
;           float var = s2 * (1.f / 512.f) - mu * mu;
;           float rstd = rsqrtf(fmaxf(var, 0.f) + 1e-5f);
; #pragma unroll
;           for (int bj = 0; bj < 2; ++bj)
; #pragma unroll
;             for (int n = 0; n < 2; ++n) {
;               float g = acc[ai][bj][m][n][j];
;               float yn = (bf2f(yv[j][bj][n]) - mu) * rstd * gn[bj][n];
;               Y[(long)(tb + j) * YS + pn * 256 + bj * 128 + wc * 32 + n * 16 + fr] = f2bf(silu_f(g) * yn);
;             }
	v_lshlrev_b32_e32 v53, 16, v184
	v_sub_f32_e32 v53, v53, v52
	v_mul_f32_e32 v53, v53, v34
	v_mul_f32_e32 v53, v149, v53
	v_mul_f32_e32 v39, v39, v56
	v_mul_f32_e32 v39, v39, v53
	v_cvt_pk_bf16_f32 v39, v39, s0
	s_waitcnt vmcnt(12)
	v_lshlrev_b32_e32 v53, 16, v185
	v_sub_f32_e32 v52, v53, v52
	v_mul_f32_e32 v34, v52, v34
	v_mul_f32_e32 v52, 0xbfb8aa3b, v35
	v_exp_f32_e32 v52, v52
	v_mul_f32_e32 v34, v148, v34
	v_add_f32_e32 v52, 1.0, v52
	v_rcp_f32_e32 v52, v52
	s_nop 0
	v_mul_f32_e32 v35, v35, v52
	s_nop 0
	v_mul_f32_e32 v34, v35, v34
	v_cvt_pk_bf16_f32 v66, v34, s0
	s_waitcnt vmcnt(10)
	v_pk_add_f32 v[34:35], v[206:207], v[208:209]
	s_nop 0
	v_pk_add_f32 v[34:35], v[34:35], v[202:203]
	v_mul_f32_e32 v51, 0xbfb8aa3b, v48
	v_pk_add_f32 v[34:35], v[34:35], v[204:205]
	v_exp_f32_e32 v51, v51
	v_pk_mul_f32 v[34:35], v[34:35], s[18:19] op_sel_hi:[1,0]
	v_add_f32_e32 v51, 1.0, v51
	v_fma_f32 v35, -v34, v34, v35
	v_max_f32_e32 v35, 0, v35
	v_add_f32_e32 v35, 0x3727c5ac, v35
	v_cmp_gt_f32_e32 vcc, s25, v35
	v_mul_f32_e32 v50, 0x4b800000, v35
	v_rcp_f32_e32 v51, v51
	v_cndmask_b32_e32 v35, v35, v50, vcc
	v_rsq_f32_e32 v35, v35
	v_mul_f32_e32 v48, v48, v51
	v_mul_f32_e32 v51, 0xbfb8aa3b, v44
	v_mul_f32_e32 v50, 0x45800000, v35
	v_cndmask_b32_e32 v50, v35, v50, vcc
	v_exp_f32_e32 v51, v51
	s_waitcnt vmcnt(9)
	v_lshlrev_b32_e32 v35, 16, v186
	v_sub_f32_e32 v35, v35, v34
	v_mul_f32_e32 v35, v35, v50
	v_mul_f32_e32 v35, v151, v35
	v_mul_f32_e32 v35, v48, v35
	v_add_f32_e32 v51, 1.0, v51
	v_rcp_f32_e32 v51, v51
	v_cvt_pk_bf16_f32 v35, v35, s0
	v_mul_f32_e32 v44, v44, v51
	v_mul_f32_e32 v51, 0xbfb8aa3b, v40
	v_exp_f32_e32 v51, v51
	s_waitcnt vmcnt(8)
	v_lshlrev_b32_e32 v48, 16, v187
	v_sub_f32_e32 v48, v48, v34
	v_mul_f32_e32 v48, v48, v50
	v_mul_f32_e32 v48, v150, v48
	v_mul_f32_e32 v44, v44, v48
	v_add_f32_e32 v51, 1.0, v51
	v_rcp_f32_e32 v51, v51
	v_cvt_pk_bf16_f32 v44, v44, s0
	v_mul_f32_e32 v40, v40, v51
	s_waitcnt vmcnt(7)
	v_lshlrev_b32_e32 v48, 16, v188
	v_sub_f32_e32 v48, v48, v34
	v_mul_f32_e32 v48, v48, v50
	v_mul_f32_e32 v48, v149, v48
	v_mul_f32_e32 v40, v40, v48
	v_cvt_pk_bf16_f32 v40, v40, s0
	s_waitcnt vmcnt(6)
	v_lshlrev_b32_e32 v48, 16, v189
	v_sub_f32_e32 v34, v48, v34
	v_mul_f32_e32 v48, 0xbfb8aa3b, v36
	v_exp_f32_e32 v48, v48
	v_mul_f32_e32 v34, v34, v50
	v_mul_f32_e32 v34, v148, v34
	v_add_f32_e32 v48, 1.0, v48
	v_rcp_f32_e32 v48, v48
	s_nop 0
	v_mul_f32_e32 v36, v36, v48
	v_mul_f32_e32 v34, v36, v34
	s_nop 0
	s_nop 0
	v_cvt_pk_bf16_f32 v34, v34, s0
	global_store_short v[60:61], v0, off
	global_store_short v[60:61], v42, off offset:32
	global_store_short v[60:61], v38, off offset:256
	global_store_short v[60:61], v46, off offset:288
	global_store_short v[62:63], v47, off
	global_store_short v[62:63], v43, off offset:32
	global_store_short v[62:63], v39, off offset:256
	global_store_short v[62:63], v66, off offset:288
	global_store_short v[64:65], v35, off
	global_store_short v[64:65], v44, off offset:32
	global_store_short v[64:65], v40, off offset:256
	global_store_short v[64:65], v34, off offset:288
	v_add_u32_e32 v38, 0xa0, v152
	s_waitcnt vmcnt(16)
	v_pk_add_f32 v[34:35], v[214:215], v[216:217]
	s_nop 0
	v_pk_add_f32 v[34:35], v[34:35], v[210:211]
	s_nop 0
	v_pk_add_f32 v[34:35], v[34:35], v[212:213]
	s_nop 0
	v_pk_mul_f32 v[34:35], v[34:35], s[18:19] op_sel_hi:[1,0]
	s_nop 0
	v_fma_f32 v0, -v34, v34, v35
	v_max_f32_e32 v0, 0, v0
	v_add_f32_e32 v0, 0x3727c5ac, v0
	v_cmp_gt_f32_e32 vcc, s25, v0
	v_mul_f32_e32 v35, 0x4b800000, v0
	s_nop 0
	v_cndmask_b32_e32 v0, v0, v35, vcc
	v_rsq_f32_e32 v0, v0
	s_nop 0
	v_mul_f32_e32 v35, 0x45800000, v0
	v_cndmask_b32_e32 v0, v0, v35, vcc
	s_waitcnt vmcnt(15)
	v_lshlrev_b32_e32 v35, 16, v190
	v_mul_f32_e32 v36, 0xbfb8aa3b, v49
	v_exp_f32_e32 v36, v36
	v_sub_f32_e32 v35, v35, v34
	v_mul_f32_e32 v35, v35, v0
	v_mul_f32_e32 v35, v151, v35
	v_add_f32_e32 v36, 1.0, v36
	v_rcp_f32_e32 v36, v36
	s_nop 0
	v_mul_f32_e32 v36, v49, v36
	v_mul_f32_e32 v35, v36, v35
	v_mul_f32_e32 v36, 0xbfb8aa3b, v45
	v_exp_f32_e32 v36, v36
	v_cvt_pk_bf16_f32 v35, v35, s0
	global_store_short v[58:59], v35, off
	s_waitcnt vmcnt(15)
	v_lshlrev_b32_e32 v35, 16, v191
	v_add_f32_e32 v36, 1.0, v36
	v_rcp_f32_e32 v36, v36
	v_sub_f32_e32 v35, v35, v34
	v_mul_f32_e32 v35, v35, v0
	v_mul_f32_e32 v35, v150, v35
	v_mul_f32_e32 v36, v45, v36
	v_mul_f32_e32 v35, v36, v35
	v_mul_f32_e32 v36, 0xbfb8aa3b, v41
	v_exp_f32_e32 v36, v36
	v_cvt_pk_bf16_f32 v35, v35, s0
	global_store_short v[58:59], v35, off offset:32
	s_waitcnt vmcnt(15)
	v_lshlrev_b32_e32 v35, 16, v192
	v_add_f32_e32 v36, 1.0, v36
	v_rcp_f32_e32 v36, v36
	v_sub_f32_e32 v35, v35, v34
	v_mul_f32_e32 v35, v35, v0
	v_mul_f32_e32 v35, v149, v35
	v_mul_f32_e32 v36, v41, v36
	v_mul_f32_e32 v35, v36, v35
	v_cvt_pk_bf16_f32 v35, v35, s0
	global_store_short v[58:59], v35, off offset:256
	s_waitcnt vmcnt(15)
; __device__ __forceinline__ float bf2f(u16 b) { return __uint_as_float(((unsigned)b) << 16); }
; __device__ __forceinline__ float silu_f(float g) { return g * __builtin_amdgcn_rcpf(1.f + __builtin_amdgcn_exp2f(-g * LOG2E)); }
; template <int EPI>
; __device__ __forceinline__ void epilogue(const Params& p, int pass, int layer, int pm, int pn,
;                                          f32x4 (&acc)[2][2][4][2], const float* xin, float* xout) {
;     ...
;         int tb = t0 + ai * 128 + wr * 64 + m * 16 + fq * 4;
;         asm volatile("" : "+v"(tb));
;         float4 s01[4], s23[4];
;         u16 yv[4][2][2];
; #pragma unroll
;         for (int j = 0; j < 4; ++j) {
;           const float4* sp = (const float4*)(stat + ((long)(tb + j) * 8 + h) * 8);
;           s01[j] = sp[0]; s23[j] = sp[1];
; #pragma unroll
;           for (int bj = 0; bj < 2; ++bj)
; #pragma unroll
;             for (int n = 0; n < 2; ++n)
;               yv[j][bj][n] = Y[(long)(tb + j) * YS + pn * 256 + bj * 128 + wc * 32 + n * 16 + fr];
;         }
; #pragma unroll
;         for (int j = 0; j < 4; ++j) {
;           float s1 = s01[j].x + s01[j].z + s23[j].x + s23[j].z, s2 = s01[j].y + s01[j].w + s23[j].y + s23[j].w;
;           float mu = s1 * (1.f / 512.f);
;           float var = s2 * (1.f / 512.f) - mu * mu;
;           float rstd = rsqrtf(fmaxf(var, 0.f) + 1e-5f);
; #pragma unroll
;           for (int bj = 0; bj < 2; ++bj)
; #pragma unroll
;             for (int n = 0; n < 2; ++n) {
;               float g = acc[ai][bj][m][n][j];
;               float yn = (bf2f(yv[j][bj][n]) - mu) * rstd * gn[bj][n];
;               Y[(long)(tb + j) * YS + pn * 256 + bj * 128 + wc * 32 + n * 16 + fr] = f2bf(silu_f(g) * yn);
;             }
	v_lshlrev_b32_e32 v35, 16, v193
	v_sub_f32_e32 v34, v35, v34
	v_mul_f32_e32 v0, v34, v0
	v_mul_f32_e32 v34, 0xbfb8aa3b, v37
	v_exp_f32_e32 v34, v34
	v_mul_f32_e32 v0, v148, v0
	v_add_f32_e32 v34, 1.0, v34
	v_rcp_f32_e32 v34, v34
	s_nop 0
	v_mul_f32_e32 v34, v37, v34
	v_mul_f32_e32 v0, v34, v0
	v_cvt_pk_bf16_f32 v0, v0, s0
	global_store_short v[58:59], v0, off offset:288
	s_nop 0
	v_ashrrev_i32_e32 v39, 31, v38
	v_lshlrev_b64 v[34:35], 8, v[38:39]
	v_lshl_add_u64 v[40:41], s[16:17], 0, v[34:35]
	global_load_dwordx4 v[50:53], v[40:41], off offset:16
	global_load_dwordx4 v[54:57], v[40:41], off
	v_mad_i64_i32 v[44:45], s[14:15], v38, s24, v[138:139]
	global_load_ushort v162, v[44:45], off
	global_load_ushort v163, v[44:45], off offset:32
	global_load_ushort v164, v[44:45], off offset:256
	global_load_ushort v165, v[44:45], off offset:288
	v_add_u32_e32 v34, 1, v38
	v_ashrrev_i32_e32 v35, 31, v34
	v_lshlrev_b64 v[36:37], 8, v[34:35]
	v_lshl_add_u64 v[36:37], s[16:17], 0, v[36:37]
	global_load_dwordx4 v[194:197], v[36:37], off offset:16
	global_load_dwordx4 v[198:201], v[36:37], off
	v_mad_i64_i32 v[46:47], s[14:15], v34, s24, v[138:139]
	global_load_ushort v166, v[46:47], off
	global_load_ushort v167, v[46:47], off offset:32
	global_load_ushort v168, v[46:47], off offset:256
	global_load_ushort v169, v[46:47], off offset:288
	v_add_u32_e32 v42, 2, v38
	v_ashrrev_i32_e32 v43, 31, v42
	v_lshlrev_b64 v[34:35], 8, v[42:43]
	v_lshl_add_u64 v[34:35], s[16:17], 0, v[34:35]
	global_load_dwordx4 v[202:205], v[34:35], off offset:16
	global_load_dwordx4 v[206:209], v[34:35], off
	v_mad_i64_i32 v[48:49], s[14:15], v42, s24, v[138:139]
	global_load_ushort v170, v[48:49], off
	global_load_ushort v171, v[48:49], off offset:32
	global_load_ushort v172, v[48:49], off offset:256
	global_load_ushort v173, v[48:49], off offset:288
	v_add_u32_e32 v42, 3, v38
	v_ashrrev_i32_e32 v43, 31, v42
	v_lshlrev_b64 v[38:39], 8, v[42:43]
	v_lshl_add_u64 v[38:39], s[16:17], 0, v[38:39]
	global_load_dwordx4 v[210:213], v[38:39], off offset:16
	global_load_dwordx4 v[214:217], v[38:39], off
	v_mad_i64_i32 v[42:43], s[14:15], v42, s24, v[138:139]
	global_load_ushort v174, v[42:43], off
	global_load_ushort v175, v[42:43], off offset:32
	global_load_ushort v176, v[42:43], off offset:256
	global_load_ushort v177, v[42:43], off offset:288
	s_waitcnt vmcnt(22)
	v_pk_add_f32 v[40:41], v[54:55], v[56:57]
	s_nop 0
	v_pk_add_f32 v[40:41], v[40:41], v[50:51]
	v_mul_f32_e32 v50, 0xbfb8aa3b, v30
	v_pk_add_f32 v[40:41], v[40:41], v[52:53]
	v_exp_f32_e32 v50, v50
	v_pk_mul_f32 v[40:41], v[40:41], s[18:19] op_sel_hi:[1,0]
	v_add_f32_e32 v50, 1.0, v50
	v_fma_f32 v0, -v40, v40, v41
	v_max_f32_e32 v0, 0, v0
	v_add_f32_e32 v0, 0x3727c5ac, v0
	v_cmp_gt_f32_e32 vcc, s25, v0
	v_mul_f32_e32 v41, 0x4b800000, v0
	v_rcp_f32_e32 v50, v50
	v_cndmask_b32_e32 v0, v0, v41, vcc
	v_rsq_f32_e32 v0, v0
	v_mul_f32_e32 v30, v30, v50
	v_mul_f32_e32 v50, 0xbfb8aa3b, v26
	v_mul_f32_e32 v41, 0x45800000, v0
	v_cndmask_b32_e32 v41, v0, v41, vcc
	v_exp_f32_e32 v50, v50
	s_waitcnt vmcnt(21)
	v_lshlrev_b32_e32 v0, 16, v162
	v_sub_f32_e32 v0, v0, v40
	v_mul_f32_e32 v0, v0, v41
	v_mul_f32_e32 v0, v151, v0
	v_mul_f32_e32 v0, v30, v0
	v_add_f32_e32 v50, 1.0, v50
	v_rcp_f32_e32 v50, v50
	v_cvt_pk_bf16_f32 v0, v0, s0
	v_mul_f32_e32 v26, v26, v50
	v_mul_f32_e32 v50, 0xbfb8aa3b, v22
	v_exp_f32_e32 v50, v50
	s_waitcnt vmcnt(20)
	v_lshlrev_b32_e32 v30, 16, v163
	v_sub_f32_e32 v30, v30, v40
	v_mul_f32_e32 v30, v30, v41
	v_mul_f32_e32 v30, v150, v30
	v_mul_f32_e32 v26, v26, v30
	v_add_f32_e32 v50, 1.0, v50
	v_rcp_f32_e32 v50, v50
	v_cvt_pk_bf16_f32 v26, v26, s0
	v_mul_f32_e32 v22, v22, v50
	s_waitcnt vmcnt(19)
	v_lshlrev_b32_e32 v30, 16, v164
	v_sub_f32_e32 v30, v30, v40
	v_mul_f32_e32 v30, v30, v41
	v_mul_f32_e32 v30, v149, v30
	v_mul_f32_e32 v22, v22, v30
	v_cvt_pk_bf16_f32 v22, v22, s0
	s_waitcnt vmcnt(18)
	v_lshlrev_b32_e32 v30, 16, v165
	v_sub_f32_e32 v30, v30, v40
	v_mul_f32_e32 v40, 0xbfb8aa3b, v18
	v_exp_f32_e32 v40, v40
	s_waitcnt vmcnt(16)
	v_pk_add_f32 v[36:37], v[198:199], v[200:201]
	v_mul_f32_e32 v30, v30, v41
	v_pk_add_f32 v[36:37], v[36:37], v[194:195]
	v_add_f32_e32 v40, 1.0, v40
	v_rcp_f32_e32 v40, v40
	v_mul_f32_e32 v30, v148, v30
	v_pk_add_f32 v[36:37], v[36:37], v[196:197]
	v_mul_f32_e32 v18, v18, v40
	v_mul_f32_e32 v18, v18, v30
	v_pk_mul_f32 v[36:37], v[36:37], s[18:19] op_sel_hi:[1,0]
	v_cvt_pk_bf16_f32 v30, v18, s0
	v_fma_f32 v18, -v36, v36, v37
	v_max_f32_e32 v18, 0, v18
	v_add_f32_e32 v18, 0x3727c5ac, v18
	v_cmp_gt_f32_e32 vcc, s25, v18
	v_mul_f32_e32 v37, 0x4b800000, v18
	v_mul_f32_e32 v40, 0xbfb8aa3b, v31
	v_cndmask_b32_e32 v18, v18, v37, vcc
	v_rsq_f32_e32 v18, v18
	v_exp_f32_e32 v40, v40
	v_mul_f32_e32 v37, 0x45800000, v18
	v_cndmask_b32_e32 v18, v18, v37, vcc
	v_add_f32_e32 v40, 1.0, v40
	v_rcp_f32_e32 v40, v40
	s_waitcnt vmcnt(15)
	v_lshlrev_b32_e32 v37, 16, v166
	v_sub_f32_e32 v37, v37, v36
	v_mul_f32_e32 v37, v37, v18
	v_mul_f32_e32 v37, v151, v37
	v_mul_f32_e32 v31, v31, v40
	v_mul_f32_e32 v31, v31, v37
	v_mul_f32_e32 v40, 0xbfb8aa3b, v27
	v_exp_f32_e32 v40, v40
	v_cvt_pk_bf16_f32 v31, v31, s0
	v_add_f32_e32 v40, 1.0, v40
	v_rcp_f32_e32 v40, v40
	s_waitcnt vmcnt(14)
	v_lshlrev_b32_e32 v37, 16, v167
	v_sub_f32_e32 v37, v37, v36
	v_mul_f32_e32 v37, v37, v18
	v_mul_f32_e32 v37, v150, v37
	v_mul_f32_e32 v27, v27, v40
	v_mul_f32_e32 v27, v27, v37
	v_mul_f32_e32 v40, 0xbfb8aa3b, v23
	v_exp_f32_e32 v40, v40
	v_cvt_pk_bf16_f32 v27, v27, s0
	v_add_f32_e32 v40, 1.0, v40
	v_rcp_f32_e32 v40, v40
	s_waitcnt vmcnt(13)
; __device__ __forceinline__ float bf2f(u16 b) { return __uint_as_float(((unsigned)b) << 16); }
; __device__ __forceinline__ float silu_f(float g) { return g * __builtin_amdgcn_rcpf(1.f + __builtin_amdgcn_exp2f(-g * LOG2E)); }
; template <int EPI>
; __device__ __forceinline__ void epilogue(const Params& p, int pass, int layer, int pm, int pn,
;                                          f32x4 (&acc)[2][2][4][2], const float* xin, float* xout) {
;     ...
;         for (int j = 0; j < 4; ++j) {
;           float s1 = s01[j].x + s01[j].z + s23[j].x + s23[j].z, s2 = s01[j].y + s01[j].w + s23[j].y + s23[j].w;
;           float mu = s1 * (1.f / 512.f);
;           float var = s2 * (1.f / 512.f) - mu * mu;
;           float rstd = rsqrtf(fmaxf(var, 0.f) + 1e-5f);
; #pragma unroll
;           for (int bj = 0; bj < 2; ++bj)
; #pragma unroll
;             for (int n = 0; n < 2; ++n) {
;               float g = acc[ai][bj][m][n][j];
;               float yn = (bf2f(yv[j][bj][n]) - mu) * rstd * gn[bj][n];
;               Y[(long)(tb + j) * YS + pn * 256 + bj * 128 + wc * 32 + n * 16 + fr] = f2bf(silu_f(g) * yn);
;             }
	v_lshlrev_b32_e32 v37, 16, v168
	v_sub_f32_e32 v37, v37, v36
	v_mul_f32_e32 v37, v37, v18
	v_mul_f32_e32 v37, v149, v37
	v_mul_f32_e32 v23, v23, v40
	v_mul_f32_e32 v23, v23, v37
	v_cvt_pk_bf16_f32 v23, v23, s0
	s_waitcnt vmcnt(12)
	v_lshlrev_b32_e32 v37, 16, v169
	v_sub_f32_e32 v36, v37, v36
	v_mul_f32_e32 v18, v36, v18
	v_mul_f32_e32 v36, 0xbfb8aa3b, v19
	v_exp_f32_e32 v36, v36
	v_mul_f32_e32 v18, v148, v18
	v_add_f32_e32 v36, 1.0, v36
	v_rcp_f32_e32 v36, v36
	s_nop 0
	v_mul_f32_e32 v19, v19, v36
	s_nop 0
	v_mul_f32_e32 v18, v19, v18
	v_cvt_pk_bf16_f32 v50, v18, s0
	s_waitcnt vmcnt(10)
	v_pk_add_f32 v[18:19], v[206:207], v[208:209]
	s_nop 0
	v_pk_add_f32 v[18:19], v[18:19], v[202:203]
	v_mul_f32_e32 v35, 0xbfb8aa3b, v32
	v_pk_add_f32 v[18:19], v[18:19], v[204:205]
	v_exp_f32_e32 v35, v35
	v_pk_mul_f32 v[18:19], v[18:19], s[18:19] op_sel_hi:[1,0]
	v_add_f32_e32 v35, 1.0, v35
	v_fma_f32 v19, -v18, v18, v19
	v_max_f32_e32 v19, 0, v19
	v_add_f32_e32 v19, 0x3727c5ac, v19
	v_cmp_gt_f32_e32 vcc, s25, v19
	v_mul_f32_e32 v34, 0x4b800000, v19
	v_rcp_f32_e32 v35, v35
	v_cndmask_b32_e32 v19, v19, v34, vcc
	v_rsq_f32_e32 v19, v19
	v_mul_f32_e32 v32, v32, v35
	v_mul_f32_e32 v35, 0xbfb8aa3b, v28
	v_mul_f32_e32 v34, 0x45800000, v19
	v_cndmask_b32_e32 v34, v19, v34, vcc
	v_exp_f32_e32 v35, v35
	s_waitcnt vmcnt(9)
	v_lshlrev_b32_e32 v19, 16, v170
	v_sub_f32_e32 v19, v19, v18
	v_mul_f32_e32 v19, v19, v34
	v_mul_f32_e32 v19, v151, v19
	v_mul_f32_e32 v19, v32, v19
	v_add_f32_e32 v35, 1.0, v35
	v_rcp_f32_e32 v35, v35
	v_cvt_pk_bf16_f32 v19, v19, s0
	v_mul_f32_e32 v28, v28, v35
	v_mul_f32_e32 v35, 0xbfb8aa3b, v24
	v_exp_f32_e32 v35, v35
	s_waitcnt vmcnt(8)
	v_lshlrev_b32_e32 v32, 16, v171
	v_sub_f32_e32 v32, v32, v18
	v_mul_f32_e32 v32, v32, v34
	v_mul_f32_e32 v32, v150, v32
	v_mul_f32_e32 v28, v28, v32
	v_add_f32_e32 v35, 1.0, v35
	v_rcp_f32_e32 v35, v35
	v_cvt_pk_bf16_f32 v28, v28, s0
	v_mul_f32_e32 v24, v24, v35
	s_waitcnt vmcnt(7)
	v_lshlrev_b32_e32 v32, 16, v172
	v_sub_f32_e32 v32, v32, v18
	v_mul_f32_e32 v32, v32, v34
	v_mul_f32_e32 v32, v149, v32
	v_mul_f32_e32 v24, v24, v32
	v_cvt_pk_bf16_f32 v24, v24, s0
	s_waitcnt vmcnt(6)
	v_lshlrev_b32_e32 v32, 16, v173
	v_sub_f32_e32 v18, v32, v18
	v_mul_f32_e32 v32, 0xbfb8aa3b, v20
	v_exp_f32_e32 v32, v32
	v_mul_f32_e32 v18, v18, v34
	v_mul_f32_e32 v18, v148, v18
	v_add_f32_e32 v32, 1.0, v32
	v_rcp_f32_e32 v32, v32
	s_nop 0
	v_mul_f32_e32 v20, v20, v32
	v_mul_f32_e32 v18, v20, v18
	s_nop 0
	s_nop 0
	v_cvt_pk_bf16_f32 v18, v18, s0
	global_store_short v[44:45], v0, off
	global_store_short v[44:45], v26, off offset:32
	global_store_short v[44:45], v22, off offset:256
	global_store_short v[44:45], v30, off offset:288
	global_store_short v[46:47], v31, off
	global_store_short v[46:47], v27, off offset:32
	global_store_short v[46:47], v23, off offset:256
	global_store_short v[46:47], v50, off offset:288
	global_store_short v[48:49], v19, off
	global_store_short v[48:49], v28, off offset:32
	global_store_short v[48:49], v24, off offset:256
	global_store_short v[48:49], v18, off offset:288
	v_add_u32_e32 v22, 0xb0, v152
	s_waitcnt vmcnt(16)
	v_pk_add_f32 v[18:19], v[214:215], v[216:217]
	s_nop 0
	v_pk_add_f32 v[18:19], v[18:19], v[210:211]
	s_nop 0
	v_pk_add_f32 v[18:19], v[18:19], v[212:213]
	s_nop 0
	v_pk_mul_f32 v[18:19], v[18:19], s[18:19] op_sel_hi:[1,0]
	s_nop 0
	v_fma_f32 v0, -v18, v18, v19
	v_max_f32_e32 v0, 0, v0
	v_add_f32_e32 v0, 0x3727c5ac, v0
	v_cmp_gt_f32_e32 vcc, s25, v0
	v_mul_f32_e32 v19, 0x4b800000, v0
	s_nop 0
	v_cndmask_b32_e32 v0, v0, v19, vcc
	v_rsq_f32_e32 v0, v0
	s_nop 0
	v_mul_f32_e32 v19, 0x45800000, v0
	v_cndmask_b32_e32 v0, v0, v19, vcc
	s_waitcnt vmcnt(15)
	v_lshlrev_b32_e32 v19, 16, v174
	v_mul_f32_e32 v20, 0xbfb8aa3b, v33
	v_exp_f32_e32 v20, v20
	v_sub_f32_e32 v19, v19, v18
	v_mul_f32_e32 v19, v19, v0
	v_mul_f32_e32 v19, v151, v19
	v_add_f32_e32 v20, 1.0, v20
	v_rcp_f32_e32 v20, v20
	s_nop 0
	v_mul_f32_e32 v20, v33, v20
	v_mul_f32_e32 v19, v20, v19
	v_mul_f32_e32 v20, 0xbfb8aa3b, v29
	v_exp_f32_e32 v20, v20
	v_cvt_pk_bf16_f32 v19, v19, s0
	global_store_short v[42:43], v19, off
	s_waitcnt vmcnt(15)
	v_lshlrev_b32_e32 v19, 16, v175
	v_add_f32_e32 v20, 1.0, v20
	v_rcp_f32_e32 v20, v20
	v_sub_f32_e32 v19, v19, v18
	v_mul_f32_e32 v19, v19, v0
	v_mul_f32_e32 v19, v150, v19
	v_mul_f32_e32 v20, v29, v20
	v_mul_f32_e32 v19, v20, v19
	v_mul_f32_e32 v20, 0xbfb8aa3b, v25
	v_exp_f32_e32 v20, v20
	v_cvt_pk_bf16_f32 v19, v19, s0
	global_store_short v[42:43], v19, off offset:32
	s_waitcnt vmcnt(15)
	v_lshlrev_b32_e32 v19, 16, v176
	v_add_f32_e32 v20, 1.0, v20
	v_rcp_f32_e32 v20, v20
	v_sub_f32_e32 v19, v19, v18
	v_mul_f32_e32 v19, v19, v0
	v_mul_f32_e32 v19, v149, v19
	v_mul_f32_e32 v20, v25, v20
	v_mul_f32_e32 v19, v20, v19
	v_cvt_pk_bf16_f32 v19, v19, s0
	global_store_short v[42:43], v19, off offset:256
	s_waitcnt vmcnt(15)
; __device__ __forceinline__ float bf2f(u16 b) { return __uint_as_float(((unsigned)b) << 16); }
; __device__ __forceinline__ float silu_f(float g) { return g * __builtin_amdgcn_rcpf(1.f + __builtin_amdgcn_exp2f(-g * LOG2E)); }
; template <int EPI>
; __device__ __forceinline__ void epilogue(const Params& p, int pass, int layer, int pm, int pn,
;                                          f32x4 (&acc)[2][2][4][2], const float* xin, float* xout) {
;     ...
;         int tb = t0 + ai * 128 + wr * 64 + m * 16 + fq * 4;
;         asm volatile("" : "+v"(tb));
;         float4 s01[4], s23[4];
;         u16 yv[4][2][2];
; #pragma unroll
;         for (int j = 0; j < 4; ++j) {
;           const float4* sp = (const float4*)(stat + ((long)(tb + j) * 8 + h) * 8);
;           s01[j] = sp[0]; s23[j] = sp[1];
; #pragma unroll
;           for (int bj = 0; bj < 2; ++bj)
; #pragma unroll
;             for (int n = 0; n < 2; ++n)
;               yv[j][bj][n] = Y[(long)(tb + j) * YS + pn * 256 + bj * 128 + wc * 32 + n * 16 + fr];
;         }
; #pragma unroll
;         for (int j = 0; j < 4; ++j) {
;           float s1 = s01[j].x + s01[j].z + s23[j].x + s23[j].z, s2 = s01[j].y + s01[j].w + s23[j].y + s23[j].w;
;           float mu = s1 * (1.f / 512.f);
;           float var = s2 * (1.f / 512.f) - mu * mu;
;           float rstd = rsqrtf(fmaxf(var, 0.f) + 1e-5f);
; #pragma unroll
;           for (int bj = 0; bj < 2; ++bj)
; #pragma unroll
;             for (int n = 0; n < 2; ++n) {
;               float g = acc[ai][bj][m][n][j];
;               float yn = (bf2f(yv[j][bj][n]) - mu) * rstd * gn[bj][n];
;               Y[(long)(tb + j) * YS + pn * 256 + bj * 128 + wc * 32 + n * 16 + fr] = f2bf(silu_f(g) * yn);
;             }
	v_lshlrev_b32_e32 v19, 16, v177
	v_sub_f32_e32 v18, v19, v18
	v_mul_f32_e32 v0, v18, v0
	v_mul_f32_e32 v18, 0xbfb8aa3b, v21
	v_exp_f32_e32 v18, v18
	v_mul_f32_e32 v0, v148, v0
	v_add_f32_e32 v18, 1.0, v18
	v_rcp_f32_e32 v18, v18
	s_nop 0
	v_mul_f32_e32 v18, v21, v18
	v_mul_f32_e32 v0, v18, v0
	v_cvt_pk_bf16_f32 v0, v0, s0
	global_store_short v[42:43], v0, off offset:288
	s_nop 0
	v_ashrrev_i32_e32 v23, 31, v22
	v_lshlrev_b64 v[18:19], 8, v[22:23]
	v_lshl_add_u64 v[24:25], s[16:17], 0, v[18:19]
	global_load_dwordx4 v[34:37], v[24:25], off offset:16
	global_load_dwordx4 v[38:41], v[24:25], off
	v_mad_i64_i32 v[28:29], s[14:15], v22, s24, v[138:139]
	global_load_ushort v178, v[28:29], off
	global_load_ushort v179, v[28:29], off offset:32
	global_load_ushort v180, v[28:29], off offset:256
	global_load_ushort v181, v[28:29], off offset:288
	v_add_u32_e32 v18, 1, v22
	v_ashrrev_i32_e32 v19, 31, v18
	v_lshlrev_b64 v[20:21], 8, v[18:19]
	v_lshl_add_u64 v[20:21], s[16:17], 0, v[20:21]
	global_load_dwordx4 v[194:197], v[20:21], off offset:16
	global_load_dwordx4 v[198:201], v[20:21], off
	v_mad_i64_i32 v[30:31], s[14:15], v18, s24, v[138:139]
	global_load_ushort v182, v[30:31], off
	global_load_ushort v183, v[30:31], off offset:32
	global_load_ushort v184, v[30:31], off offset:256
	global_load_ushort v185, v[30:31], off offset:288
	v_add_u32_e32 v26, 2, v22
	v_ashrrev_i32_e32 v27, 31, v26
	v_lshlrev_b64 v[18:19], 8, v[26:27]
	v_lshl_add_u64 v[18:19], s[16:17], 0, v[18:19]
	global_load_dwordx4 v[202:205], v[18:19], off offset:16
	global_load_dwordx4 v[206:209], v[18:19], off
	v_mad_i64_i32 v[32:33], s[14:15], v26, s24, v[138:139]
	global_load_ushort v186, v[32:33], off
	global_load_ushort v187, v[32:33], off offset:32
	global_load_ushort v188, v[32:33], off offset:256
	global_load_ushort v189, v[32:33], off offset:288
	v_add_u32_e32 v26, 3, v22
	v_ashrrev_i32_e32 v27, 31, v26
	v_lshlrev_b64 v[22:23], 8, v[26:27]
	v_lshl_add_u64 v[22:23], s[16:17], 0, v[22:23]
	global_load_dwordx4 v[210:213], v[22:23], off offset:16
	global_load_dwordx4 v[214:217], v[22:23], off
	v_mad_i64_i32 v[26:27], s[14:15], v26, s24, v[138:139]
	global_load_ushort v190, v[26:27], off
	global_load_ushort v191, v[26:27], off offset:32
	global_load_ushort v192, v[26:27], off offset:256
	global_load_ushort v193, v[26:27], off offset:288
	s_mov_b32 s14, s6
	s_waitcnt vmcnt(22)
	v_pk_add_f32 v[24:25], v[38:39], v[40:41]
	s_nop 0
	v_pk_add_f32 v[24:25], v[24:25], v[34:35]
	v_mul_f32_e32 v34, 0xbfb8aa3b, v14
	v_pk_add_f32 v[24:25], v[24:25], v[36:37]
	v_exp_f32_e32 v34, v34
	v_pk_mul_f32 v[24:25], v[24:25], s[18:19] op_sel_hi:[1,0]
	v_add_f32_e32 v34, 1.0, v34
	v_fma_f32 v0, -v24, v24, v25
	v_max_f32_e32 v0, 0, v0
	v_add_f32_e32 v0, 0x3727c5ac, v0
	v_cmp_gt_f32_e32 vcc, s25, v0
	v_mul_f32_e32 v25, 0x4b800000, v0
	v_rcp_f32_e32 v34, v34
	v_cndmask_b32_e32 v0, v0, v25, vcc
	v_rsq_f32_e32 v0, v0
	v_mul_f32_e32 v14, v14, v34
	v_mul_f32_e32 v34, 0xbfb8aa3b, v10
	v_mul_f32_e32 v25, 0x45800000, v0
	v_cndmask_b32_e32 v25, v0, v25, vcc
	v_exp_f32_e32 v34, v34
	s_waitcnt vmcnt(21)
	v_lshlrev_b32_e32 v0, 16, v178
	v_sub_f32_e32 v0, v0, v24
	v_mul_f32_e32 v0, v0, v25
	v_mul_f32_e32 v0, v151, v0
	v_mul_f32_e32 v0, v14, v0
	v_add_f32_e32 v34, 1.0, v34
	v_rcp_f32_e32 v34, v34
	v_cvt_pk_bf16_f32 v0, v0, s0
	v_mul_f32_e32 v10, v10, v34
	v_mul_f32_e32 v34, 0xbfb8aa3b, v6
	v_exp_f32_e32 v34, v34
	s_waitcnt vmcnt(20)
	v_lshlrev_b32_e32 v14, 16, v179
	v_sub_f32_e32 v14, v14, v24
	v_mul_f32_e32 v14, v14, v25
	v_mul_f32_e32 v14, v150, v14
	v_mul_f32_e32 v10, v10, v14
	v_add_f32_e32 v34, 1.0, v34
	v_rcp_f32_e32 v34, v34
	v_cvt_pk_bf16_f32 v10, v10, s0
	v_mul_f32_e32 v6, v6, v34
	s_waitcnt vmcnt(19)
	v_lshlrev_b32_e32 v14, 16, v180
	v_sub_f32_e32 v14, v14, v24
	v_mul_f32_e32 v14, v14, v25
	v_mul_f32_e32 v14, v149, v14
	v_mul_f32_e32 v6, v6, v14
	v_cvt_pk_bf16_f32 v6, v6, s0
	s_waitcnt vmcnt(18)
	v_lshlrev_b32_e32 v14, 16, v181
	v_sub_f32_e32 v14, v14, v24
	v_mul_f32_e32 v24, 0xbfb8aa3b, v2
	v_exp_f32_e32 v24, v24
	s_waitcnt vmcnt(16)
	v_pk_add_f32 v[20:21], v[198:199], v[200:201]
	v_mul_f32_e32 v14, v14, v25
	v_pk_add_f32 v[20:21], v[20:21], v[194:195]
	v_add_f32_e32 v24, 1.0, v24
	v_rcp_f32_e32 v24, v24
	v_mul_f32_e32 v14, v148, v14
	v_pk_add_f32 v[20:21], v[20:21], v[196:197]
	v_mul_f32_e32 v2, v2, v24
	v_mul_f32_e32 v2, v2, v14
	v_pk_mul_f32 v[20:21], v[20:21], s[18:19] op_sel_hi:[1,0]
	v_cvt_pk_bf16_f32 v14, v2, s0
	v_fma_f32 v2, -v20, v20, v21
	v_max_f32_e32 v2, 0, v2
	v_add_f32_e32 v2, 0x3727c5ac, v2
	v_cmp_gt_f32_e32 vcc, s25, v2
	v_mul_f32_e32 v21, 0x4b800000, v2
	v_mul_f32_e32 v24, 0xbfb8aa3b, v15
	v_cndmask_b32_e32 v2, v2, v21, vcc
	v_rsq_f32_e32 v2, v2
	v_exp_f32_e32 v24, v24
	v_mul_f32_e32 v21, 0x45800000, v2
	v_cndmask_b32_e32 v2, v2, v21, vcc
	v_add_f32_e32 v24, 1.0, v24
	v_rcp_f32_e32 v24, v24
	s_waitcnt vmcnt(15)
	v_lshlrev_b32_e32 v21, 16, v182
	v_sub_f32_e32 v21, v21, v20
	v_mul_f32_e32 v21, v21, v2
	v_mul_f32_e32 v21, v151, v21
	v_mul_f32_e32 v15, v15, v24
	v_mul_f32_e32 v15, v15, v21
	v_mul_f32_e32 v24, 0xbfb8aa3b, v11
	v_exp_f32_e32 v24, v24
	v_cvt_pk_bf16_f32 v15, v15, s0
	v_add_f32_e32 v24, 1.0, v24
	v_rcp_f32_e32 v24, v24
	s_waitcnt vmcnt(14)
; __device__ __forceinline__ float bf2f(u16 b) { return __uint_as_float(((unsigned)b) << 16); }
; __device__ __forceinline__ float silu_f(float g) { return g * __builtin_amdgcn_rcpf(1.f + __builtin_amdgcn_exp2f(-g * LOG2E)); }
; template <int EPI>
; __device__ __forceinline__ void epilogue(const Params& p, int pass, int layer, int pm, int pn,
;                                          f32x4 (&acc)[2][2][4][2], const float* xin, float* xout) {
;     ...
;         for (int j = 0; j < 4; ++j) {
;           float s1 = s01[j].x + s01[j].z + s23[j].x + s23[j].z, s2 = s01[j].y + s01[j].w + s23[j].y + s23[j].w;
;           float mu = s1 * (1.f / 512.f);
;           float var = s2 * (1.f / 512.f) - mu * mu;
;           float rstd = rsqrtf(fmaxf(var, 0.f) + 1e-5f);
; #pragma unroll
;           for (int bj = 0; bj < 2; ++bj)
; #pragma unroll
;             for (int n = 0; n < 2; ++n) {
;               float g = acc[ai][bj][m][n][j];
;               float yn = (bf2f(yv[j][bj][n]) - mu) * rstd * gn[bj][n];
;               Y[(long)(tb + j) * YS + pn * 256 + bj * 128 + wc * 32 + n * 16 + fr] = f2bf(silu_f(g) * yn);
;             }
	v_lshlrev_b32_e32 v21, 16, v183
	v_sub_f32_e32 v21, v21, v20
	v_mul_f32_e32 v21, v21, v2
	v_mul_f32_e32 v21, v150, v21
	v_mul_f32_e32 v11, v11, v24
	v_mul_f32_e32 v11, v11, v21
	v_mul_f32_e32 v24, 0xbfb8aa3b, v7
	v_exp_f32_e32 v24, v24
	v_cvt_pk_bf16_f32 v11, v11, s0
	v_add_f32_e32 v24, 1.0, v24
	v_rcp_f32_e32 v24, v24
	s_waitcnt vmcnt(13)
	v_lshlrev_b32_e32 v21, 16, v184
	v_sub_f32_e32 v21, v21, v20
	v_mul_f32_e32 v21, v21, v2
	v_mul_f32_e32 v21, v149, v21
	v_mul_f32_e32 v7, v7, v24
	v_mul_f32_e32 v7, v7, v21
	v_cvt_pk_bf16_f32 v7, v7, s0
	s_waitcnt vmcnt(12)
	v_lshlrev_b32_e32 v21, 16, v185
	v_sub_f32_e32 v20, v21, v20
	v_mul_f32_e32 v2, v20, v2
	v_mul_f32_e32 v20, 0xbfb8aa3b, v3
	v_exp_f32_e32 v20, v20
	v_mul_f32_e32 v2, v148, v2
	v_add_f32_e32 v20, 1.0, v20
	v_rcp_f32_e32 v20, v20
	s_nop 0
	v_mul_f32_e32 v3, v3, v20
	s_nop 0
	v_mul_f32_e32 v2, v3, v2
	v_cvt_pk_bf16_f32 v34, v2, s0
	s_waitcnt vmcnt(10)
	v_pk_add_f32 v[2:3], v[206:207], v[208:209]
	s_nop 0
	v_pk_add_f32 v[2:3], v[2:3], v[202:203]
	v_mul_f32_e32 v19, 0xbfb8aa3b, v16
	v_pk_add_f32 v[2:3], v[2:3], v[204:205]
	v_exp_f32_e32 v19, v19
	v_pk_mul_f32 v[2:3], v[2:3], s[18:19] op_sel_hi:[1,0]
	v_add_f32_e32 v19, 1.0, v19
	v_fma_f32 v3, -v2, v2, v3
	v_max_f32_e32 v3, 0, v3
	v_add_f32_e32 v3, 0x3727c5ac, v3
	v_cmp_gt_f32_e32 vcc, s25, v3
	v_mul_f32_e32 v18, 0x4b800000, v3
	v_rcp_f32_e32 v19, v19
	v_cndmask_b32_e32 v3, v3, v18, vcc
	v_rsq_f32_e32 v3, v3
	v_mul_f32_e32 v16, v16, v19
	v_mul_f32_e32 v19, 0xbfb8aa3b, v12
	v_mul_f32_e32 v18, 0x45800000, v3
	v_cndmask_b32_e32 v18, v3, v18, vcc
	v_exp_f32_e32 v19, v19
	s_waitcnt vmcnt(9)
	v_lshlrev_b32_e32 v3, 16, v186
	v_sub_f32_e32 v3, v3, v2
	v_mul_f32_e32 v3, v3, v18
	v_mul_f32_e32 v3, v151, v3
	v_mul_f32_e32 v3, v16, v3
	v_add_f32_e32 v19, 1.0, v19
	v_rcp_f32_e32 v19, v19
	v_cvt_pk_bf16_f32 v3, v3, s0
	v_mul_f32_e32 v12, v12, v19
	v_mul_f32_e32 v19, 0xbfb8aa3b, v8
	v_exp_f32_e32 v19, v19
	s_waitcnt vmcnt(8)
	v_lshlrev_b32_e32 v16, 16, v187
	v_sub_f32_e32 v16, v16, v2
	v_mul_f32_e32 v16, v16, v18
	v_mul_f32_e32 v16, v150, v16
	v_mul_f32_e32 v12, v12, v16
	v_add_f32_e32 v19, 1.0, v19
	v_rcp_f32_e32 v19, v19
	v_cvt_pk_bf16_f32 v12, v12, s0
	v_mul_f32_e32 v8, v8, v19
	s_waitcnt vmcnt(7)
	v_lshlrev_b32_e32 v16, 16, v188
	v_sub_f32_e32 v16, v16, v2
	v_mul_f32_e32 v16, v16, v18
	v_mul_f32_e32 v16, v149, v16
	v_mul_f32_e32 v8, v8, v16
	v_cvt_pk_bf16_f32 v8, v8, s0
	s_waitcnt vmcnt(6)
	v_lshlrev_b32_e32 v16, 16, v189
	v_sub_f32_e32 v2, v16, v2
	v_mul_f32_e32 v16, 0xbfb8aa3b, v4
	v_exp_f32_e32 v16, v16
	v_mul_f32_e32 v2, v2, v18
	v_mul_f32_e32 v2, v148, v2
	v_add_f32_e32 v16, 1.0, v16
	v_rcp_f32_e32 v16, v16
	s_nop 0
	v_mul_f32_e32 v4, v4, v16
	v_mul_f32_e32 v2, v4, v2
	s_nop 0
	s_nop 0
	v_cvt_pk_bf16_f32 v2, v2, s0
	global_store_short v[28:29], v0, off
	global_store_short v[28:29], v10, off offset:32
	global_store_short v[28:29], v6, off offset:256
	global_store_short v[28:29], v14, off offset:288
	global_store_short v[30:31], v15, off
	global_store_short v[30:31], v11, off offset:32
	global_store_short v[30:31], v7, off offset:256
	global_store_short v[30:31], v34, off offset:288
	global_store_short v[32:33], v3, off
	global_store_short v[32:33], v12, off offset:32
	global_store_short v[32:33], v8, off offset:256
	global_store_short v[32:33], v2, off offset:288
	s_waitcnt vmcnt(16)
	v_pk_add_f32 v[2:3], v[214:215], v[216:217]
	s_nop 0
	v_pk_add_f32 v[2:3], v[2:3], v[210:211]
	s_nop 0
	v_pk_add_f32 v[2:3], v[2:3], v[212:213]
	s_nop 0
	v_pk_mul_f32 v[2:3], v[2:3], s[18:19] op_sel_hi:[1,0]
	s_nop 0
	v_fma_f32 v0, -v2, v2, v3
	v_max_f32_e32 v0, 0, v0
	v_add_f32_e32 v0, 0x3727c5ac, v0
	v_cmp_gt_f32_e32 vcc, s25, v0
	v_mul_f32_e32 v3, 0x4b800000, v0
	s_nop 0
	v_cndmask_b32_e32 v0, v0, v3, vcc
	v_rsq_f32_e32 v0, v0
	s_nop 0
	v_mul_f32_e32 v3, 0x45800000, v0
	v_cndmask_b32_e32 v0, v0, v3, vcc
	s_waitcnt vmcnt(15)
	v_lshlrev_b32_e32 v3, 16, v190
	v_mul_f32_e32 v4, 0xbfb8aa3b, v17
	v_exp_f32_e32 v4, v4
	v_sub_f32_e32 v3, v3, v2
	v_mul_f32_e32 v3, v3, v0
	v_mul_f32_e32 v3, v151, v3
	v_add_f32_e32 v4, 1.0, v4
	v_rcp_f32_e32 v4, v4
	s_and_b64 vcc, exec, s[4:5]
	v_mul_f32_e32 v4, v17, v4
	v_mul_f32_e32 v3, v4, v3
	v_mul_f32_e32 v4, 0xbfb8aa3b, v13
	v_exp_f32_e32 v4, v4
	v_cvt_pk_bf16_f32 v3, v3, s0
	global_store_short v[26:27], v3, off
	s_waitcnt vmcnt(15)
	v_lshlrev_b32_e32 v3, 16, v191
	v_add_f32_e32 v4, 1.0, v4
	v_rcp_f32_e32 v4, v4
	v_sub_f32_e32 v3, v3, v2
	v_mul_f32_e32 v3, v3, v0
	v_mul_f32_e32 v3, v150, v3
	v_mul_f32_e32 v4, v13, v4
	v_mul_f32_e32 v3, v4, v3
	v_mul_f32_e32 v4, 0xbfb8aa3b, v9
	v_exp_f32_e32 v4, v4
	v_cvt_pk_bf16_f32 v3, v3, s0
	global_store_short v[26:27], v3, off offset:32
	s_waitcnt vmcnt(15)
	v_lshlrev_b32_e32 v3, 16, v192
	v_add_f32_e32 v4, 1.0, v4
	v_rcp_f32_e32 v4, v4
	v_sub_f32_e32 v3, v3, v2
	v_mul_f32_e32 v3, v3, v0
	v_mul_f32_e32 v3, v149, v3
	v_mul_f32_e32 v4, v9, v4
	v_mul_f32_e32 v3, v4, v3
	v_cvt_pk_bf16_f32 v3, v3, s0
	global_store_short v[26:27], v3, off offset:256
	s_waitcnt vmcnt(15)
	v_lshlrev_b32_e32 v3, 16, v193
	v_sub_f32_e32 v2, v3, v2
	v_mul_f32_e32 v0, v2, v0
	v_mul_f32_e32 v2, 0xbfb8aa3b, v5
	v_exp_f32_e32 v2, v2
	v_mul_f32_e32 v0, v148, v0
	v_add_f32_e32 v2, 1.0, v2
	v_rcp_f32_e32 v2, v2
	s_nop 0
	v_mul_f32_e32 v2, v5, v2
	v_mul_f32_e32 v0, v2, v0
	v_cvt_pk_bf16_f32 v0, v0, s0
	global_store_short v[26:27], v0, off offset:288
	s_cbranch_vccnz .LBB0_66
